# v10 + packed fma for in-place softmax score scaling in attention loops
# baseline (speedup 1.0000x reference)
; #define LAS __attribute__((address_space(3)))
; DI void partialSM(f32x16& p0, f32x16& p1, float& m_reg, float& mn, float& alpha) {
;     ...
;     else { mn = fmaxf(m_reg, pmax); alpha = __builtin_amdgcn_exp2f((m_reg - mn) * CL2); m_reg = mn; }
;     const float mnC = -mn * CL2;
; #pragma unroll
;     for (int r = 0; r < 16; ++r) p0[r] = fmaf(p0[r], CL2, mnC);
; #pragma unroll
;     for (int r = 0; r < 16; ++r) p1[r] = fmaf(p1[r], CL2, mnC);
; #pragma unroll
;     for (int r = 0; r < 16; ++r) p0[r] = __builtin_amdgcn_exp2f(p0[r]);
; }
; DI void finishSM(f32x16& p0, f32x16& p1, float alpha, float& l_reg, bf16x8& pa0, bf16x8& pa1, bf16x8& pa2, bf16x8& pa3) {
; #pragma unroll
;     for (int r = 0; r < 16; ++r) p1[r] = __builtin_amdgcn_exp2f(p1[r]);
;     float ps = 0.f;
; #pragma unroll
;     for (int r = 0; r < 16; ++r) ps += p0[r];
; #pragma unroll
;     for (int r = 0; r < 16; ++r) ps += p1[r];
;     { auto rr = __builtin_amdgcn_permlane32_swap(__float_as_uint(ps), __float_as_uint(ps), false, false); ps = __uint_as_float(rr[0]) + __uint_as_float(rr[1]); }
;     l_reg = l_reg * alpha + ps;
;     ...
;     ATT_PK4(p0, 0, pa0); ATT_PK4(p0, 8, pa1); ATT_PK4(p1, 0, pa2); ATT_PK4(p1, 8, pa3);
;     ...
; }
; DI void qkt64(f32x16& p0, f32x16& p1, const LAS unsigned char* Kb, const bf16x8 (&qr)[4], int r32, int hi) {
; #pragma unroll
;     for (int r = 0; r < 16; ++r) { p0[r] = 0.f; p1[r] = 0.f; }
; #pragma unroll
;     for (int d0 = 0; d0 < 4; ++d0) { const int cb = d0 * 32 + hi * 16;
;         const bf16x8 b0 = *(const LAS bf16x8*)(Kb + r32 * KROWB + cb), b1 = *(const LAS bf16x8*)(Kb + (32 + r32) * KROWB + cb);
;         p0 = __builtin_amdgcn_mfma_f32_32x32x16_bf16(b0, qr[d0], p0, 0, 0, 0);
;         p1 = __builtin_amdgcn_mfma_f32_32x32x16_bf16(b1, qr[d0], p1, 0, 0, 0); }
.LBB0_398:
	v_cndmask_b32_e64 v184, v138, v142, s[4:5]
	v_mul_f32_e32 v185, 0xbe38aa3b, v184
	v_pk_fma_f32 v[80:81], v[80:81], s[90:91], v[184:185] op_sel:[0,0,1] op_sel_hi:[1,0,1]
	v_pk_fma_f32 v[82:83], v[82:83], s[90:91], v[184:185] op_sel:[0,0,1] op_sel_hi:[1,0,1]
	v_pk_fma_f32 v[84:85], v[84:85], s[90:91], v[184:185] op_sel:[0,0,1] op_sel_hi:[1,0,1]
	v_pk_fma_f32 v[86:87], v[86:87], s[90:91], v[184:185] op_sel:[0,0,1] op_sel_hi:[1,0,1]
	v_pk_fma_f32 v[88:89], v[88:89], s[90:91], v[184:185] op_sel:[0,0,1] op_sel_hi:[1,0,1]
	v_pk_fma_f32 v[90:91], v[90:91], s[90:91], v[184:185] op_sel:[0,0,1] op_sel_hi:[1,0,1]
	v_pk_fma_f32 v[92:93], v[92:93], s[90:91], v[184:185] op_sel:[0,0,1] op_sel_hi:[1,0,1]
	v_pk_fma_f32 v[94:95], v[94:95], s[90:91], v[184:185] op_sel:[0,0,1] op_sel_hi:[1,0,1]
	v_exp_f32_e32 v138, v80
	v_exp_f32_e32 v153, v81
	v_exp_f32_e32 v139, v82
	v_exp_f32_e32 v152, v83
	v_exp_f32_e32 v140, v84
	v_exp_f32_e32 v151, v85
	v_exp_f32_e32 v141, v86
	v_exp_f32_e32 v150, v87
	v_exp_f32_e32 v142, v88
	v_exp_f32_e32 v149, v89
	v_exp_f32_e32 v143, v90
	v_exp_f32_e32 v148, v91
	v_exp_f32_e32 v144, v92
	v_exp_f32_e32 v147, v93
	v_exp_f32_e32 v145, v94
	v_exp_f32_e32 v146, v95
	v_fmamk_f32 v194, v64, 0x3e38aa3b, v185
	v_fmamk_f32 v195, v65, 0x3e38aa3b, v185
	v_fmamk_f32 v202, v66, 0x3e38aa3b, v185
	v_fmamk_f32 v203, v67, 0x3e38aa3b, v185
	v_fmamk_f32 v204, v68, 0x3e38aa3b, v185
	v_fmamk_f32 v187, v69, 0x3e38aa3b, v185
	v_fmamk_f32 v188, v70, 0x3e38aa3b, v185
	v_fmamk_f32 v189, v71, 0x3e38aa3b, v185
	v_fmamk_f32 v190, v72, 0x3e38aa3b, v185
	v_fmamk_f32 v191, v73, 0x3e38aa3b, v185
	v_fmamk_f32 v192, v74, 0x3e38aa3b, v185
	v_fmamk_f32 v193, v75, 0x3e38aa3b, v185
	v_fmamk_f32 v186, v76, 0x3e38aa3b, v185
	v_fmamk_f32 v205, v77, 0x3e38aa3b, v185
	v_fmamk_f32 v206, v78, 0x3e38aa3b, v185
	v_fmac_f32_e32 v185, 0x3e38aa3b, v79
	s_waitcnt lgkmcnt(0)
	s_barrier
	ds_read_b128 v[64:67], v178 offset:4608
	ds_read_b128 v[68:71], v178
	ds_read_b128 v[208:211], v178 offset:32
	ds_read_b128 v[212:215], v178 offset:4640
	v_exp_f32_e32 v194, v194
	v_exp_f32_e32 v195, v195
	s_waitcnt lgkmcnt(2)
	v_mfma_f32_32x32x16_bf16 v[80:95], v[68:71], v[110:113], 0
	v_exp_f32_e32 v202, v202
	v_exp_f32_e32 v203, v203
	v_exp_f32_e32 v204, v204
	v_exp_f32_e32 v187, v187
	v_exp_f32_e32 v188, v188
	v_exp_f32_e32 v189, v189
	v_exp_f32_e32 v190, v190
	v_mfma_f32_32x32x16_bf16 v[64:79], v[64:67], v[110:113], 0
	v_exp_f32_e32 v191, v191
	v_exp_f32_e32 v192, v192
	v_exp_f32_e32 v193, v193
	v_exp_f32_e32 v207, v186
	v_exp_f32_e32 v205, v205
	v_exp_f32_e32 v206, v206
	s_waitcnt lgkmcnt(1)
	v_mfma_f32_32x32x16_bf16 v[80:95], v[208:211], v[106:109], v[80:95]
	s_waitcnt lgkmcnt(0)
	v_mfma_f32_32x32x16_bf16 v[64:79], v[212:215], v[106:109], v[64:79]
	ds_read_b128 v[208:211], v178 offset:64
	ds_read_b128 v[212:215], v178 offset:4672
	s_waitcnt lgkmcnt(1)
	v_mfma_f32_32x32x16_bf16 v[80:95], v[208:211], v[102:105], v[80:95]
	s_waitcnt lgkmcnt(0)
	v_mfma_f32_32x32x16_bf16 v[64:79], v[212:215], v[102:105], v[64:79]
	ds_read_b128 v[208:211], v178 offset:96
	ds_read_b128 v[212:215], v178 offset:4704
	s_waitcnt lgkmcnt(1)
	v_mfma_f32_32x32x16_bf16 v[80:95], v[208:211], v[98:101], v[80:95]
	v_exp_f32_e32 v208, v185
	v_add_f32_e32 v185, 0, v138
	v_add_f32_e32 v185, v153, v185
	v_add_f32_e32 v185, v139, v185
	v_add_f32_e32 v185, v152, v185
	v_add_f32_e32 v185, v140, v185
	v_add_f32_e32 v185, v151, v185
	v_add_f32_e32 v185, v141, v185
	v_add_f32_e32 v185, v150, v185
	v_add_f32_e32 v185, v142, v185
	v_add_f32_e32 v185, v149, v185
	v_add_f32_e32 v185, v143, v185
	v_add_f32_e32 v185, v148, v185
	v_add_f32_e32 v185, v144, v185
	v_add_f32_e32 v185, v147, v185
	v_add_f32_e32 v185, v145, v185
	v_add_f32_e32 v185, v146, v185
	v_add_f32_e32 v185, v194, v185
	v_add_f32_e32 v185, v195, v185
	v_add_f32_e32 v185, v202, v185
	v_add_f32_e32 v185, v203, v185
	v_add_f32_e32 v185, v204, v185
	v_add_f32_e32 v185, v187, v185
	v_add_f32_e32 v185, v188, v185
	v_add_f32_e32 v185, v189, v185
	v_add_f32_e32 v185, v190, v185
	v_add_f32_e32 v185, v191, v185
	s_waitcnt lgkmcnt(0)
	v_mfma_f32_32x32x16_bf16 v[64:79], v[212:215], v[98:101], v[64:79]
	v_add_f32_e32 v185, v192, v185
	v_add_f32_e32 v185, v193, v185
	v_add_f32_e32 v185, v207, v185
	v_add_f32_e32 v185, v205, v185
	v_add_f32_e32 v185, v206, v185
	v_add_f32_e32 v185, v208, v185
	v_mov_b32_e32 v186, v185
	v_cvt_pk_bf16_f32 v138, v138, v153
	v_cvt_pk_bf16_f32 v139, v139, v152
	v_cvt_pk_bf16_f32 v140, v140, v151
	v_cvt_pk_bf16_f32 v141, v141, v150
	v_cvt_pk_bf16_f32 v142, v142, v149
	v_cvt_pk_bf16_f32 v143, v143, v148
	v_cvt_pk_bf16_f32 v144, v144, v147
	v_cvt_pk_bf16_f32 v145, v145, v146
	v_cvt_pk_bf16_f32 v146, v194, v195
	v_cvt_pk_bf16_f32 v147, v202, v203
	v_cvt_pk_bf16_f32 v148, v204, v187
	v_cvt_pk_bf16_f32 v149, v188, v189
	v_cvt_pk_bf16_f32 v150, v190, v191
	v_cvt_pk_bf16_f32 v151, v192, v193
	v_cvt_pk_bf16_f32 v152, v207, v205
	v_cvt_pk_bf16_f32 v153, v206, v208
	s_nop 1
	v_permlane32_swap_b32_e32 v185, v186
	v_permlane32_swap_b32_e32 v138, v140
	v_permlane32_swap_b32_e32 v139, v141
	v_permlane32_swap_b32_e32 v142, v144
	v_permlane32_swap_b32_e32 v143, v145
	v_permlane32_swap_b32_e32 v146, v148
	v_permlane32_swap_b32_e32 v147, v149
	v_permlane32_swap_b32_e32 v150, v152
	v_permlane32_swap_b32_e32 v151, v153
	s_cmp_gt_u32 s48, 64
	s_cselect_b64 s[0:1], -1, 0
	s_and_b64 vcc, exec, s[0:1]
	s_cbranch_vccnz .LBB0_400
	v_add_co_u32_e32 v114, vcc, 0xc4e0000, v168
	s_nop 1
	v_addc_co_u32_e32 v115, vcc, 0, v169, vcc
	v_add_co_u32_e32 v118, vcc, 0xc4e0000, v166
	global_load_dwordx4 v[114:117], v[114:115], off offset:1024
	s_nop 0
	v_addc_co_u32_e32 v119, vcc, 0, v167, vcc
	v_add_co_u32_e32 v122, vcc, 0xc53c000, v166
	s_nop 1
	v_addc_co_u32_e32 v123, vcc, 0, v167, vcc
	global_load_dwordx4 v[118:121], v[118:119], off offset:2048
	s_nop 0
	global_load_dwordx4 v[122:125], v[122:123], off offset:2048

; #define PP_WRITEO() do { *(LAS bf16x8*)(Kl + KBUF + kl) = ksO; *(LAS bf16x8*)(Vl + VBUF + vl0) = v0O; *(LAS bf16x8*)(Vl + VBUF + vl1) = v1O; } while (0)
; #define PP_RESC(a) do { if (__any((a) < 1.f)) { if (hi == 0) wsf[r32] = (a); asm volatile("s_waitcnt lgkmcnt(0)" ::: "memory"); \
;     _Pragma("unroll") for (int r = 0; r < 16; ++r) { const float a_ = wsf[crow(r, hi)]; _Pragma("unroll") for (int d = 0; d < 4; ++d) o[d][r] *= a_; } } } while (0)
; DI void partialSM(f32x16& p0, f32x16& p1, float& m_reg, float& mn, float& alpha) {
;     ...
;     if (__builtin_expect(__all(pmax - m_reg <= THRS), 1)) { mn = m_reg; alpha = 1.f; }
;     else { mn = fmaxf(m_reg, pmax); alpha = __builtin_amdgcn_exp2f((m_reg - mn) * CL2); m_reg = mn; }
;     const float mnC = -mn * CL2;
; #pragma unroll
;     for (int r = 0; r < 16; ++r) p0[r] = fmaf(p0[r], CL2, mnC);
; #pragma unroll
;     for (int r = 0; r < 16; ++r) p1[r] = fmaf(p1[r], CL2, mnC);
; #pragma unroll
;     for (int r = 0; r < 16; ++r) p0[r] = __builtin_amdgcn_exp2f(p0[r]);
; DI void attn_pass_pipe(LAS unsigned char* lds, const bf16_t* __restrict__ Zb, size_t qoff, int kcol, int vcol, int t0, int NT, f32x16 (&o)[4], float& l_out) {
;     ...
;         pv128(o, vb0 + VBUF, pa0, pa1, pa2, pa3); partialSM(pA0, pA1, m_reg, mnA, alA);
;         __syncthreads(); PP_WRITEO();
;         PP_RESC(alA); __syncthreads();
;     }
.LBB0_404:
	v_cndmask_b32_e64 v142, v138, v184, s[4:5]
	v_mul_f32_e32 v126, 0xbe38aa3b, v142
	v_mov_b32_e32 v127, v126
	v_pk_fma_f32 v[80:81], v[80:81], s[90:91], v[126:127] op_sel_hi:[1,0,0]
	v_pk_fma_f32 v[82:83], v[82:83], s[90:91], v[126:127] op_sel_hi:[1,0,0]
	v_pk_fma_f32 v[84:85], v[84:85], s[90:91], v[126:127] op_sel_hi:[1,0,0]
	v_pk_fma_f32 v[86:87], v[86:87], s[90:91], v[126:127] op_sel_hi:[1,0,0]
	v_pk_fma_f32 v[88:89], v[88:89], s[90:91], v[126:127] op_sel_hi:[1,0,0]
	v_pk_fma_f32 v[90:91], v[90:91], s[90:91], v[126:127] op_sel_hi:[1,0,0]
	v_pk_fma_f32 v[92:93], v[92:93], s[90:91], v[126:127] op_sel_hi:[1,0,0]
	v_fmamk_f32 v94, v94, 0x3e38aa3b, v126
	v_fmac_f32_e32 v127, 0x3e38aa3b, v95
	v_exp_f32_e32 v152, v80
	v_exp_f32_e32 v168, v81
	v_exp_f32_e32 v153, v82
	v_exp_f32_e32 v169, v83
	v_exp_f32_e32 v166, v84
	v_exp_f32_e32 v184, v85
	v_exp_f32_e32 v167, v86
	v_exp_f32_e32 v187, v87
	v_exp_f32_e32 v144, v88
	v_exp_f32_e32 v148, v89
	v_exp_f32_e32 v145, v90
	v_exp_f32_e32 v149, v91
	v_exp_f32_e32 v146, v92
	v_exp_f32_e32 v150, v93
	v_exp_f32_e32 v147, v94
	v_exp_f32_e32 v151, v127
	v_pk_fma_f32 v[138:139], v[64:65], s[90:91], v[126:127] op_sel_hi:[1,0,0]
	v_add_f32_e32 v64, v181, v182
	v_fmac_f32_e32 v64, v180, v173
	v_add_f32_e32 v173, v185, v186
	v_pk_fma_f32 v[136:137], v[66:67], s[90:91], v[126:127] op_sel_hi:[1,0,0]
	v_pk_fma_f32 v[134:135], v[68:69], s[90:91], v[126:127] op_sel_hi:[1,0,0]
	v_pk_fma_f32 v[130:131], v[70:71], s[90:91], v[126:127] op_sel_hi:[1,0,0]
	v_pk_fma_f32 v[128:129], v[72:73], s[90:91], v[126:127] op_sel_hi:[1,0,0]
	v_pk_fma_f32 v[140:141], v[74:75], s[90:91], v[126:127] op_sel_hi:[1,0,0]
	v_pk_fma_f32 v[132:133], v[76:77], s[90:91], v[126:127] op_sel_hi:[1,0,0]
	v_pk_fma_f32 v[126:127], v[78:79], s[90:91], v[126:127] op_sel_hi:[1,0,0]
	v_fmac_f32_e32 v173, v64, v183
	s_add_i32 s48, s48, 2
	v_lshl_add_u64 v[158:159], v[158:159], 0, s[92:93]
	v_lshl_add_u64 v[162:163], v[162:163], 0, s[92:93]
	s_and_b64 vcc, exec, s[0:1]
	s_waitcnt lgkmcnt(0)
	s_barrier
	s_cbranch_vccnz .LBB0_406
	v_mov_b32_e32 v180, v143
	s_branch .LBB0_394

; #define PP_RESC(a) do { if (__any((a) < 1.f)) { if (hi == 0) wsf[r32] = (a); asm volatile("s_waitcnt lgkmcnt(0)" ::: "memory"); \
;     _Pragma("unroll") for (int r = 0; r < 16; ++r) { const float a_ = wsf[crow(r, hi)]; _Pragma("unroll") for (int d = 0; d < 4; ++d) o[d][r] *= a_; } } } while (0)
; #define PP_SB() __builtin_amdgcn_sched_barrier(0)
; DI void partialSM(f32x16& p0, f32x16& p1, float& m_reg, float& mn, float& alpha) {
;     ...
;     const float mnC = -mn * CL2;
; #pragma unroll
;     for (int r = 0; r < 16; ++r) p0[r] = fmaf(p0[r], CL2, mnC);
; #pragma unroll
;     for (int r = 0; r < 16; ++r) p1[r] = fmaf(p1[r], CL2, mnC);
; #pragma unroll
;     for (int r = 0; r < 16; ++r) p0[r] = __builtin_amdgcn_exp2f(p0[r]);
; }
; DI void finishSM(f32x16& p0, f32x16& p1, float alpha, float& l_reg, bf16x8& pa0, bf16x8& pa1, bf16x8& pa2, bf16x8& pa3) {
; #pragma unroll
;     for (int r = 0; r < 16; ++r) p1[r] = __builtin_amdgcn_exp2f(p1[r]);
;     float ps = 0.f;
; #pragma unroll
;     for (int r = 0; r < 16; ++r) ps += p0[r];
; #pragma unroll
;     for (int r = 0; r < 16; ++r) ps += p1[r];
;     { auto rr = __builtin_amdgcn_permlane32_swap(__float_as_uint(ps), __float_as_uint(ps), false, false); ps = __uint_as_float(rr[0]) + __uint_as_float(rr[1]); }
;     l_reg = l_reg * alpha + ps;
;     ...
;     ATT_PK4(p0, 0, pa0); ATT_PK4(p0, 8, pa1); ATT_PK4(p1, 0, pa2); ATT_PK4(p1, 8, pa3);
; DI void attn_pass_pipe(LAS unsigned char* lds, const bf16_t* __restrict__ Zb, size_t qoff, int kcol, int vcol, int t0, int NT, f32x16 (&o)[4], float& l_out) {
;     ...
;     PP_SB(); qkt64(pB0, pB1, Kl + KBUF, qr, r32, hi);
;     finishSM(pA0, pA1, alA, l_reg, pa0, pa1, pa2, pa3); PP_SB();
;     pv128(o, vb0, pa0, pa1, pa2, pa3); partialSM(pB0, pB1, m_reg, mnB, alB);
;     __syncthreads(); PP_RESC(alB);
;     finishSM(pB0, pB1, alB, l_reg, pa0, pa1, pa2, pa3); PP_SB();
;     pv128(o, vb0 + VBUF, pa0, pa1, pa2, pa3);
;     __builtin_amdgcn_s_setprio(0);
;     __syncthreads();
.LBB0_410:
	v_cndmask_b32_e64 v96, v101, v142, s[4:5]
	v_mul_f32_e32 v96, 0xbe38aa3b, v96
	v_pk_fma_f32 v[80:81], v[80:81], s[90:91], v[96:97] op_sel_hi:[1,0,0]
	v_exp_f32_e32 v80, v80
	v_fmamk_f32 v82, v82, 0x3e38aa3b, v96
	v_exp_f32_e32 v81, v81
	v_fmamk_f32 v83, v83, 0x3e38aa3b, v96
	v_exp_f32_e32 v82, v82
	v_fmamk_f32 v95, v95, 0x3e38aa3b, v96
	v_fmamk_f32 v94, v94, 0x3e38aa3b, v96
	v_fmamk_f32 v93, v93, 0x3e38aa3b, v96
	v_fmamk_f32 v92, v92, 0x3e38aa3b, v96
	v_fmamk_f32 v91, v91, 0x3e38aa3b, v96
	v_fmamk_f32 v90, v90, 0x3e38aa3b, v96
	v_fmamk_f32 v89, v89, 0x3e38aa3b, v96
	v_fmamk_f32 v88, v88, 0x3e38aa3b, v96
	v_fmamk_f32 v87, v87, 0x3e38aa3b, v96
	v_fmamk_f32 v86, v86, 0x3e38aa3b, v96
	v_fmamk_f32 v85, v85, 0x3e38aa3b, v96
	v_fmamk_f32 v84, v84, 0x3e38aa3b, v96
	v_exp_f32_e32 v83, v83
	v_fmamk_f32 v79, v79, 0x3e38aa3b, v96
	v_fmamk_f32 v78, v78, 0x3e38aa3b, v96
	v_fmamk_f32 v77, v77, 0x3e38aa3b, v96
	v_fmamk_f32 v76, v76, 0x3e38aa3b, v96
	v_fmamk_f32 v75, v75, 0x3e38aa3b, v96
	v_fmamk_f32 v74, v74, 0x3e38aa3b, v96
	v_fmamk_f32 v73, v73, 0x3e38aa3b, v96
	v_fmamk_f32 v72, v72, 0x3e38aa3b, v96
	v_fmamk_f32 v71, v71, 0x3e38aa3b, v96
	v_fmamk_f32 v70, v70, 0x3e38aa3b, v96
	v_fmamk_f32 v69, v69, 0x3e38aa3b, v96
	v_fmamk_f32 v68, v68, 0x3e38aa3b, v96
	v_fmamk_f32 v67, v67, 0x3e38aa3b, v96
	v_fmamk_f32 v66, v66, 0x3e38aa3b, v96
	v_fmamk_f32 v65, v65, 0x3e38aa3b, v96
	v_fmac_f32_e32 v96, 0x3e38aa3b, v64
	v_exp_f32_e32 v84, v84
	v_exp_f32_e32 v64, v96
	v_exp_f32_e32 v96, v65
	v_add_f32_e32 v65, 0, v80
	v_exp_f32_e32 v85, v85
	v_add_f32_e32 v65, v81, v65
	v_exp_f32_e32 v86, v86
	v_add_f32_e32 v65, v82, v65
	v_exp_f32_e32 v87, v87
	v_add_f32_e32 v65, v83, v65
	v_exp_f32_e32 v88, v88
	v_add_f32_e32 v65, v84, v65
	v_exp_f32_e32 v89, v89
	v_add_f32_e32 v65, v85, v65
	v_exp_f32_e32 v90, v90
	v_add_f32_e32 v65, v86, v65
	v_exp_f32_e32 v91, v91
	v_add_f32_e32 v65, v87, v65
	v_exp_f32_e32 v92, v92
	v_add_f32_e32 v65, v88, v65
	v_exp_f32_e32 v93, v93
	v_add_f32_e32 v65, v89, v65
	v_exp_f32_e32 v94, v94
	v_add_f32_e32 v65, v90, v65
	v_exp_f32_e32 v95, v95
	v_add_f32_e32 v65, v91, v65
	v_add_f32_e32 v65, v92, v65
	v_add_f32_e32 v65, v93, v65
	v_exp_f32_e32 v66, v66
	v_add_f32_e32 v65, v94, v65
	v_exp_f32_e32 v101, v67
	v_add_f32_e32 v65, v95, v65
	v_exp_f32_e32 v102, v68
	v_add_f32_e32 v65, v64, v65
	v_exp_f32_e32 v103, v69
	v_add_f32_e32 v65, v96, v65
	v_exp_f32_e32 v104, v70
	v_add_f32_e32 v65, v66, v65
	v_exp_f32_e32 v105, v71
	v_add_f32_e32 v65, v101, v65
	v_exp_f32_e32 v106, v72
	v_add_f32_e32 v65, v102, v65
	v_exp_f32_e32 v107, v73
	v_add_f32_e32 v65, v103, v65
	v_exp_f32_e32 v108, v74
	v_add_f32_e32 v65, v104, v65
	v_exp_f32_e32 v109, v75
	v_add_f32_e32 v65, v105, v65
	v_exp_f32_e32 v110, v76
	v_add_f32_e32 v65, v106, v65
	v_exp_f32_e32 v111, v77
	v_add_f32_e32 v65, v107, v65
	v_exp_f32_e32 v112, v78
	v_add_f32_e32 v65, v108, v65
	v_exp_f32_e32 v113, v79
	v_add_f32_e32 v65, v109, v65
	v_add_f32_e32 v65, v110, v65
	v_add_f32_e32 v65, v111, v65
	v_add_f32_e32 v65, v112, v65
	v_add_f32_e32 v65, v113, v65
	v_mov_b32_e32 v67, v65
	v_cvt_pk_bf16_f32 v68, v80, v81
	v_cvt_pk_bf16_f32 v69, v82, v83
	v_cvt_pk_bf16_f32 v70, v84, v85
	v_cvt_pk_bf16_f32 v71, v86, v87
	s_nop 1
	v_permlane32_swap_b32_e32 v65, v67
	v_permlane32_swap_b32_e32 v68, v70
	v_permlane32_swap_b32_e32 v69, v71
	v_cvt_pk_bf16_f32 v72, v88, v89
	v_cvt_pk_bf16_f32 v73, v90, v91
	v_cvt_pk_bf16_f32 v74, v92, v93
	v_cvt_pk_bf16_f32 v75, v94, v95
	v_cvt_pk_bf16_f32 v76, v64, v96
	v_cvt_pk_bf16_f32 v77, v66, v101
	v_cvt_pk_bf16_f32 v78, v102, v103
	v_cvt_pk_bf16_f32 v79, v104, v105
	v_cvt_pk_bf16_f32 v80, v106, v107
	v_cvt_pk_bf16_f32 v81, v108, v109
	v_cvt_pk_bf16_f32 v82, v110, v111
	v_cvt_pk_bf16_f32 v83, v112, v113
	s_nop 0
	v_permlane32_swap_b32_e32 v72, v74
	v_permlane32_swap_b32_e32 v73, v75
	v_permlane32_swap_b32_e32 v76, v78
	v_permlane32_swap_b32_e32 v77, v79
	v_permlane32_swap_b32_e32 v80, v82
	v_permlane32_swap_b32_e32 v81, v83
	ds_read_b64_tr_b16 v[84:85], v174 offset:0
	ds_read_b64_tr_b16 v[86:87], v174 offset:0x800
	ds_read_b64_tr_b16 v[88:89], v174 offset:0x1000
	ds_read_b64_tr_b16 v[90:91], v174 offset:0x1800
	ds_read_b64_tr_b16 v[92:93], v174 offset:0x2000
	ds_read_b64_tr_b16 v[94:95], v174 offset:0x2800
	ds_read_b64_tr_b16 v[102:103], v174 offset:0x3000
	ds_read_b64_tr_b16 v[104:105], v174 offset:0x3800
	s_waitcnt lgkmcnt(0)
	s_nop 0
	v_mfma_f32_32x32x16_bf16 v[48:63], v[68:71], v[84:87], v[48:63]
	ds_read_b64_tr_b16 v[84:85], v174 offset:0x200
	ds_read_b64_tr_b16 v[86:87], v174 offset:0xa00
	v_mfma_f32_32x32x16_bf16 v[48:63], v[72:75], v[88:91], v[48:63]
	ds_read_b64_tr_b16 v[88:89], v174 offset:0x1200
	ds_read_b64_tr_b16 v[90:91], v174 offset:0x1a00
	v_mfma_f32_32x32x16_bf16 v[48:63], v[76:79], v[92:95], v[48:63]
	ds_read_b64_tr_b16 v[92:93], v174 offset:0x2200
	ds_read_b64_tr_b16 v[94:95], v174 offset:0x2a00
	v_mfma_f32_32x32x16_bf16 v[48:63], v[80:83], v[102:105], v[48:63]
	ds_read_b64_tr_b16 v[102:103], v174 offset:0x3200
	ds_read_b64_tr_b16 v[104:105], v174 offset:0x3a00
	s_waitcnt lgkmcnt(0)
	v_mfma_f32_32x32x16_bf16 v[32:47], v[68:71], v[84:87], v[32:47]
	ds_read_b64_tr_b16 v[84:85], v174 offset:0x400
	ds_read_b64_tr_b16 v[86:87], v174 offset:0xc00
	v_mfma_f32_32x32x16_bf16 v[32:47], v[72:75], v[88:91], v[32:47]
	ds_read_b64_tr_b16 v[88:89], v174 offset:0x1400
	ds_read_b64_tr_b16 v[90:91], v174 offset:0x1c00
	v_mfma_f32_32x32x16_bf16 v[32:47], v[76:79], v[92:95], v[32:47]
	ds_read_b64_tr_b16 v[92:93], v174 offset:0x2400
	ds_read_b64_tr_b16 v[94:95], v174 offset:0x2c00
	v_mfma_f32_32x32x16_bf16 v[32:47], v[80:83], v[102:105], v[32:47]
	ds_read_b64_tr_b16 v[102:103], v174 offset:0x3400
	ds_read_b64_tr_b16 v[104:105], v174 offset:0x3c00
	s_waitcnt lgkmcnt(0)
	v_mfma_f32_32x32x16_bf16 v[16:31], v[68:71], v[84:87], v[16:31]
	ds_read_b64_tr_b16 v[84:85], v174 offset:0x600
	ds_read_b64_tr_b16 v[86:87], v174 offset:0xe00
	v_mfma_f32_32x32x16_bf16 v[16:31], v[72:75], v[88:91], v[16:31]
	ds_read_b64_tr_b16 v[88:89], v174 offset:0x1600
	ds_read_b64_tr_b16 v[90:91], v174 offset:0x1e00
	v_mfma_f32_32x32x16_bf16 v[16:31], v[76:79], v[92:95], v[16:31]
	ds_read_b64_tr_b16 v[92:93], v174 offset:0x2600
	ds_read_b64_tr_b16 v[94:95], v174 offset:0x2e00
	v_mfma_f32_32x32x16_bf16 v[16:31], v[80:83], v[102:105], v[16:31]
	ds_read_b64_tr_b16 v[102:103], v174 offset:0x3600
	ds_read_b64_tr_b16 v[104:105], v174 offset:0x3e00
	s_waitcnt lgkmcnt(0)
	v_mfma_f32_32x32x16_bf16 v[0:15], v[68:71], v[84:87], v[0:15]
	v_mfma_f32_32x32x16_bf16 v[0:15], v[72:75], v[88:91], v[0:15]
	v_mfma_f32_32x32x16_bf16 v[0:15], v[76:79], v[92:95], v[0:15]
	v_mfma_f32_32x32x16_bf16 v[0:15], v[80:83], v[102:105], v[0:15]
	s_setprio 0
	v_mov_b32_e32 v64, v196
	s_barrier
; #define LAS __attribute__((address_space(3)))
; DI void row_rcp(LAS unsigned char* lds, float l, float (&rli)[16]) {
;     int tid_ = threadIdx.x; asm volatile("" : "+v"(tid_));
;     const int tid = tid_, wid = tid >> 6, lane = tid & 63, r32 = lane & 31, hi = lane >> 5;
;     LAS float* wsf = (LAS float*)(lds + L_WS) + wid * 64;
;     if (hi == 0) wsf[32 + r32] = l;
	s_nop 0
	v_bfe_u32 v68, v64, 5, 1
	v_and_b32_e32 v66, 0x3fffffc0, v64
	v_lshl_add_u32 v69, v66, 2, 0
	v_cmp_eq_u32_e32 vcc, 0, v68
	s_and_saveexec_b64 s[0:1], vcc
	s_cbranch_execz .LBB0_412
	v_and_b32_e32 v64, 31, v64
	v_lshl_add_u32 v70, v64, 2, v69
	v_mul_f32_e32 v64, v173, v143
	v_add_f32_e32 v66, v98, v99
	v_pk_add_f32 v[64:65], v[64:65], v[66:67]
	s_nop 0
	v_fmac_f32_e32 v65, v64, v100
	ds_write_b32 v70, v65 offset:51328

; #define LAS __attribute__((address_space(3)))
; DI void partialSM(f32x16& p0, f32x16& p1, float& m_reg, float& mn, float& alpha) {
;     ...
;     else { mn = fmaxf(m_reg, pmax); alpha = __builtin_amdgcn_exp2f((m_reg - mn) * CL2); m_reg = mn; }
;     const float mnC = -mn * CL2;
; #pragma unroll
;     for (int r = 0; r < 16; ++r) p0[r] = fmaf(p0[r], CL2, mnC);
; #pragma unroll
;     for (int r = 0; r < 16; ++r) p1[r] = fmaf(p1[r], CL2, mnC);
; #pragma unroll
;     for (int r = 0; r < 16; ++r) p0[r] = __builtin_amdgcn_exp2f(p0[r]);
; }
; DI void finishSM(f32x16& p0, f32x16& p1, float alpha, float& l_reg, bf16x8& pa0, bf16x8& pa1, bf16x8& pa2, bf16x8& pa3) {
; #pragma unroll
;     for (int r = 0; r < 16; ++r) p1[r] = __builtin_amdgcn_exp2f(p1[r]);
;     float ps = 0.f;
; #pragma unroll
;     for (int r = 0; r < 16; ++r) ps += p0[r];
; #pragma unroll
;     for (int r = 0; r < 16; ++r) ps += p1[r];
;     { auto rr = __builtin_amdgcn_permlane32_swap(__float_as_uint(ps), __float_as_uint(ps), false, false); ps = __uint_as_float(rr[0]) + __uint_as_float(rr[1]); }
;     l_reg = l_reg * alpha + ps;
;     ...
;     ATT_PK4(p0, 0, pa0); ATT_PK4(p0, 8, pa1); ATT_PK4(p1, 0, pa2); ATT_PK4(p1, 8, pa3);
;     ...
; }
; DI void qkt64(f32x16& p0, f32x16& p1, const LAS unsigned char* Kb, const bf16x8 (&qr)[4], int r32, int hi) {
; #pragma unroll
;     for (int r = 0; r < 16; ++r) { p0[r] = 0.f; p1[r] = 0.f; }
; #pragma unroll
;     for (int d0 = 0; d0 < 4; ++d0) { const int cb = d0 * 32 + hi * 16;
;         const bf16x8 b0 = *(const LAS bf16x8*)(Kb + r32 * KROWB + cb), b1 = *(const LAS bf16x8*)(Kb + (32 + r32) * KROWB + cb);
;         p0 = __builtin_amdgcn_mfma_f32_32x32x16_bf16(b0, qr[d0], p0, 0, 0, 0);
;         p1 = __builtin_amdgcn_mfma_f32_32x32x16_bf16(b1, qr[d0], p1, 0, 0, 0); }
.LBB0_419:
	v_cndmask_b32_e64 v187, v138, v142, s[4:5]
	v_mul_f32_e32 v188, 0xbe38aa3b, v187
	v_pk_fma_f32 v[80:81], v[80:81], s[90:91], v[188:189] op_sel_hi:[1,0,0]
	v_pk_fma_f32 v[82:83], v[82:83], s[90:91], v[188:189] op_sel_hi:[1,0,0]
	v_pk_fma_f32 v[84:85], v[84:85], s[90:91], v[188:189] op_sel_hi:[1,0,0]
	v_pk_fma_f32 v[86:87], v[86:87], s[90:91], v[188:189] op_sel_hi:[1,0,0]
	v_pk_fma_f32 v[88:89], v[88:89], s[90:91], v[188:189] op_sel_hi:[1,0,0]
	v_pk_fma_f32 v[90:91], v[90:91], s[90:91], v[188:189] op_sel_hi:[1,0,0]
	v_pk_fma_f32 v[92:93], v[92:93], s[90:91], v[188:189] op_sel_hi:[1,0,0]
	v_pk_fma_f32 v[94:95], v[94:95], s[90:91], v[188:189] op_sel_hi:[1,0,0]
	v_exp_f32_e32 v138, v80
	v_exp_f32_e32 v153, v81
	v_exp_f32_e32 v139, v82
	v_exp_f32_e32 v152, v83
	v_exp_f32_e32 v140, v84
	v_exp_f32_e32 v151, v85
	v_exp_f32_e32 v141, v86
	v_exp_f32_e32 v150, v87
	v_exp_f32_e32 v142, v88
	v_exp_f32_e32 v149, v89
	v_exp_f32_e32 v143, v90
	v_exp_f32_e32 v148, v91
	v_exp_f32_e32 v144, v92
	v_exp_f32_e32 v147, v93
	v_exp_f32_e32 v145, v94
	v_exp_f32_e32 v146, v95
	v_fmamk_f32 v203, v64, 0x3e38aa3b, v188
	v_fmamk_f32 v204, v65, 0x3e38aa3b, v188
	v_fmamk_f32 v205, v66, 0x3e38aa3b, v188
	v_fmamk_f32 v206, v67, 0x3e38aa3b, v188
	v_fmamk_f32 v207, v68, 0x3e38aa3b, v188
	v_fmamk_f32 v190, v69, 0x3e38aa3b, v188
	v_fmamk_f32 v191, v70, 0x3e38aa3b, v188
	v_fmamk_f32 v192, v71, 0x3e38aa3b, v188
	v_fmamk_f32 v193, v72, 0x3e38aa3b, v188
	v_fmamk_f32 v194, v73, 0x3e38aa3b, v188
	v_fmamk_f32 v195, v74, 0x3e38aa3b, v188
	v_fmamk_f32 v202, v75, 0x3e38aa3b, v188
	v_fmamk_f32 v189, v76, 0x3e38aa3b, v188
	v_fmamk_f32 v208, v77, 0x3e38aa3b, v188
	v_fmamk_f32 v209, v78, 0x3e38aa3b, v188
	v_fmac_f32_e32 v188, 0x3e38aa3b, v79
	s_waitcnt lgkmcnt(0)
	s_barrier
	ds_read_b128 v[64:67], v178 offset:4608
	ds_read_b128 v[68:71], v178
	ds_read_b128 v[210:213], v178 offset:32
	ds_read_b128 v[214:217], v178 offset:4640
	v_exp_f32_e32 v203, v203
	v_exp_f32_e32 v204, v204
	s_waitcnt lgkmcnt(2)
	v_mfma_f32_32x32x16_bf16 v[80:95], v[68:71], v[110:113], 0
	v_exp_f32_e32 v205, v205
	v_exp_f32_e32 v206, v206
	v_exp_f32_e32 v207, v207
	v_exp_f32_e32 v190, v190
	v_exp_f32_e32 v191, v191
	v_exp_f32_e32 v192, v192
	v_exp_f32_e32 v193, v193
	v_mfma_f32_32x32x16_bf16 v[64:79], v[64:67], v[110:113], 0
	v_exp_f32_e32 v194, v194
	v_exp_f32_e32 v195, v195
	v_exp_f32_e32 v202, v202
	v_exp_f32_e32 v208, v208
	v_exp_f32_e32 v209, v209
	s_waitcnt lgkmcnt(1)
	v_mfma_f32_32x32x16_bf16 v[80:95], v[210:213], v[106:109], v[80:95]
	s_waitcnt lgkmcnt(0)
	v_mfma_f32_32x32x16_bf16 v[64:79], v[214:217], v[106:109], v[64:79]
	ds_read_b128 v[210:213], v178 offset:64
	ds_read_b128 v[214:217], v178 offset:4672
	s_waitcnt lgkmcnt(1)
	v_mfma_f32_32x32x16_bf16 v[80:95], v[210:213], v[102:105], v[80:95]
	s_waitcnt lgkmcnt(0)
	v_mfma_f32_32x32x16_bf16 v[64:79], v[214:217], v[102:105], v[64:79]
	ds_read_b128 v[210:213], v178 offset:96
	ds_read_b128 v[214:217], v178 offset:4704
	s_waitcnt lgkmcnt(1)
	v_mfma_f32_32x32x16_bf16 v[80:95], v[210:213], v[98:101], v[80:95]
	v_exp_f32_e32 v211, v188
	v_add_f32_e32 v188, 0, v138
	v_add_f32_e32 v188, v153, v188
	v_add_f32_e32 v188, v139, v188
	v_add_f32_e32 v188, v152, v188
	v_add_f32_e32 v188, v140, v188
	v_add_f32_e32 v188, v151, v188
	v_add_f32_e32 v188, v141, v188
	v_add_f32_e32 v188, v150, v188
	v_add_f32_e32 v188, v142, v188
	v_add_f32_e32 v188, v149, v188
	v_add_f32_e32 v188, v143, v188
	v_add_f32_e32 v188, v148, v188
	v_add_f32_e32 v188, v144, v188
	v_add_f32_e32 v188, v147, v188
	v_add_f32_e32 v188, v145, v188
	v_add_f32_e32 v188, v146, v188
	v_add_f32_e32 v188, v203, v188
	v_add_f32_e32 v188, v204, v188
	v_add_f32_e32 v188, v205, v188
	v_add_f32_e32 v188, v206, v188
	v_add_f32_e32 v188, v207, v188
	v_add_f32_e32 v188, v190, v188
	v_add_f32_e32 v188, v191, v188
	v_add_f32_e32 v188, v192, v188
	v_exp_f32_e32 v210, v189
	v_add_f32_e32 v188, v193, v188
	v_add_f32_e32 v188, v194, v188
	s_waitcnt lgkmcnt(0)
	v_mfma_f32_32x32x16_bf16 v[64:79], v[214:217], v[98:101], v[64:79]
	v_add_f32_e32 v188, v195, v188
	v_add_f32_e32 v188, v202, v188
	v_add_f32_e32 v188, v210, v188
	v_add_f32_e32 v188, v208, v188
	v_add_f32_e32 v188, v209, v188
	v_add_f32_e32 v188, v211, v188
	v_mov_b32_e32 v189, v188
	v_cvt_pk_bf16_f32 v138, v138, v153
	v_cvt_pk_bf16_f32 v139, v139, v152
	v_cvt_pk_bf16_f32 v140, v140, v151
	v_cvt_pk_bf16_f32 v141, v141, v150
	v_cvt_pk_bf16_f32 v142, v142, v149
	v_cvt_pk_bf16_f32 v143, v143, v148
	v_cvt_pk_bf16_f32 v144, v144, v147
	v_cvt_pk_bf16_f32 v145, v145, v146
	v_cvt_pk_bf16_f32 v146, v203, v204
	v_cvt_pk_bf16_f32 v147, v205, v206
	v_cvt_pk_bf16_f32 v148, v207, v190
	v_cvt_pk_bf16_f32 v149, v191, v192
	v_cvt_pk_bf16_f32 v150, v193, v194
	v_cvt_pk_bf16_f32 v151, v195, v202
	v_cvt_pk_bf16_f32 v152, v210, v208
	v_cvt_pk_bf16_f32 v153, v209, v211
	s_nop 1
	v_permlane32_swap_b32_e32 v188, v189
	v_permlane32_swap_b32_e32 v138, v140
	v_permlane32_swap_b32_e32 v139, v141
	v_permlane32_swap_b32_e32 v142, v144
	v_permlane32_swap_b32_e32 v143, v145
	v_permlane32_swap_b32_e32 v146, v148
	v_permlane32_swap_b32_e32 v147, v149
	v_permlane32_swap_b32_e32 v150, v152
	v_permlane32_swap_b32_e32 v151, v153
	s_cmp_gt_u32 s48, 64
	s_cselect_b64 s[0:1], -1, 0
	s_and_b64 vcc, exec, s[0:1]
	s_cbranch_vccnz .LBB0_421
	v_add_co_u32_e32 v114, vcc, 0xc4e0000, v170
	s_nop 1
	v_addc_co_u32_e32 v115, vcc, 0, v171, vcc
	v_add_co_u32_e32 v118, vcc, 0xc4e0000, v168
	global_load_dwordx4 v[114:117], v[114:115], off offset:1152
	s_nop 0
	v_addc_co_u32_e32 v119, vcc, 0, v169, vcc
	v_add_co_u32_e32 v122, vcc, 0xc53c000, v168
	s_nop 1
	v_addc_co_u32_e32 v123, vcc, 0, v169, vcc
	global_load_dwordx4 v[118:121], v[118:119], off offset:2048
	s_nop 0
	global_load_dwordx4 v[122:125], v[122:123], off offset:2048

; #define PP_WRITEO() do { *(LAS bf16x8*)(Kl + KBUF + kl) = ksO; *(LAS bf16x8*)(Vl + VBUF + vl0) = v0O; *(LAS bf16x8*)(Vl + VBUF + vl1) = v1O; } while (0)
; #define PP_RESC(a) do { if (__any((a) < 1.f)) { if (hi == 0) wsf[r32] = (a); asm volatile("s_waitcnt lgkmcnt(0)" ::: "memory"); \
;     _Pragma("unroll") for (int r = 0; r < 16; ++r) { const float a_ = wsf[crow(r, hi)]; _Pragma("unroll") for (int d = 0; d < 4; ++d) o[d][r] *= a_; } } } while (0)
; DI void partialSM(f32x16& p0, f32x16& p1, float& m_reg, float& mn, float& alpha) {
;     ...
;     if (__builtin_expect(__all(pmax - m_reg <= THRS), 1)) { mn = m_reg; alpha = 1.f; }
;     else { mn = fmaxf(m_reg, pmax); alpha = __builtin_amdgcn_exp2f((m_reg - mn) * CL2); m_reg = mn; }
;     const float mnC = -mn * CL2;
; #pragma unroll
;     for (int r = 0; r < 16; ++r) p0[r] = fmaf(p0[r], CL2, mnC);
; #pragma unroll
;     for (int r = 0; r < 16; ++r) p1[r] = fmaf(p1[r], CL2, mnC);
; #pragma unroll
;     for (int r = 0; r < 16; ++r) p0[r] = __builtin_amdgcn_exp2f(p0[r]);
; DI void attn_pass_pipe(LAS unsigned char* lds, const bf16_t* __restrict__ Zb, size_t qoff, int kcol, int vcol, int t0, int NT, f32x16 (&o)[4], float& l_out) {
;     ...
;         pv128(o, vb0 + VBUF, pa0, pa1, pa2, pa3); partialSM(pA0, pA1, m_reg, mnA, alA);
;         __syncthreads(); PP_WRITEO();
;         PP_RESC(alA); __syncthreads();
;     }
.LBB0_425:
	v_cndmask_b32_e64 v142, v138, v187, s[4:5]
	v_mul_f32_e32 v126, 0xbe38aa3b, v142
	v_mov_b32_e32 v127, v126
	v_pk_fma_f32 v[80:81], v[80:81], s[90:91], v[126:127] op_sel_hi:[1,0,0]
	v_pk_fma_f32 v[82:83], v[82:83], s[90:91], v[126:127] op_sel_hi:[1,0,0]
	v_pk_fma_f32 v[84:85], v[84:85], s[90:91], v[126:127] op_sel_hi:[1,0,0]
	v_pk_fma_f32 v[86:87], v[86:87], s[90:91], v[126:127] op_sel_hi:[1,0,0]
	v_pk_fma_f32 v[88:89], v[88:89], s[90:91], v[126:127] op_sel_hi:[1,0,0]
	v_pk_fma_f32 v[90:91], v[90:91], s[90:91], v[126:127] op_sel_hi:[1,0,0]
	v_pk_fma_f32 v[92:93], v[92:93], s[90:91], v[126:127] op_sel_hi:[1,0,0]
	v_fmamk_f32 v94, v94, 0x3e38aa3b, v126
	v_fmac_f32_e32 v127, 0x3e38aa3b, v95
	v_exp_f32_e32 v152, v80
	v_exp_f32_e32 v170, v81
	v_exp_f32_e32 v153, v82
	v_exp_f32_e32 v171, v83
	v_exp_f32_e32 v168, v84
	v_exp_f32_e32 v187, v85
	v_exp_f32_e32 v169, v86
	v_exp_f32_e32 v190, v87
	v_exp_f32_e32 v144, v88
	v_exp_f32_e32 v148, v89
	v_exp_f32_e32 v145, v90
	v_exp_f32_e32 v149, v91
	v_exp_f32_e32 v146, v92
	v_exp_f32_e32 v150, v93
	v_exp_f32_e32 v147, v94
	v_exp_f32_e32 v151, v127
	v_pk_fma_f32 v[138:139], v[64:65], s[90:91], v[126:127] op_sel_hi:[1,0,0]
	v_add_f32_e32 v64, v184, v185
	v_fmac_f32_e32 v64, v183, v176
	v_add_f32_e32 v176, v188, v189
	v_pk_fma_f32 v[136:137], v[66:67], s[90:91], v[126:127] op_sel_hi:[1,0,0]
	v_pk_fma_f32 v[134:135], v[68:69], s[90:91], v[126:127] op_sel_hi:[1,0,0]
	v_pk_fma_f32 v[130:131], v[70:71], s[90:91], v[126:127] op_sel_hi:[1,0,0]
	v_pk_fma_f32 v[128:129], v[72:73], s[90:91], v[126:127] op_sel_hi:[1,0,0]
	v_pk_fma_f32 v[140:141], v[74:75], s[90:91], v[126:127] op_sel_hi:[1,0,0]
	v_pk_fma_f32 v[132:133], v[76:77], s[90:91], v[126:127] op_sel_hi:[1,0,0]
	v_pk_fma_f32 v[126:127], v[78:79], s[90:91], v[126:127] op_sel_hi:[1,0,0]
	v_fmac_f32_e32 v176, v64, v186
	s_add_i32 s48, s48, 2
	v_lshl_add_u64 v[164:165], v[164:165], 0, s[92:93]
	v_lshl_add_u64 v[166:167], v[166:167], 0, s[92:93]
	s_and_b64 vcc, exec, s[0:1]
	s_waitcnt lgkmcnt(0)
	s_barrier
	s_cbranch_vccnz .LBB0_427
	v_mov_b32_e32 v183, v143
	s_branch .LBB0_415

; #define PP_RESC(a) do { if (__any((a) < 1.f)) { if (hi == 0) wsf[r32] = (a); asm volatile("s_waitcnt lgkmcnt(0)" ::: "memory"); \
;     _Pragma("unroll") for (int r = 0; r < 16; ++r) { const float a_ = wsf[crow(r, hi)]; _Pragma("unroll") for (int d = 0; d < 4; ++d) o[d][r] *= a_; } } } while (0)
; #define PP_SB() __builtin_amdgcn_sched_barrier(0)
; DI void partialSM(f32x16& p0, f32x16& p1, float& m_reg, float& mn, float& alpha) {
;     ...
;     const float mnC = -mn * CL2;
; #pragma unroll
;     for (int r = 0; r < 16; ++r) p0[r] = fmaf(p0[r], CL2, mnC);
; #pragma unroll
;     for (int r = 0; r < 16; ++r) p1[r] = fmaf(p1[r], CL2, mnC);
; #pragma unroll
;     for (int r = 0; r < 16; ++r) p0[r] = __builtin_amdgcn_exp2f(p0[r]);
; }
; DI void finishSM(f32x16& p0, f32x16& p1, float alpha, float& l_reg, bf16x8& pa0, bf16x8& pa1, bf16x8& pa2, bf16x8& pa3) {
; #pragma unroll
;     for (int r = 0; r < 16; ++r) p1[r] = __builtin_amdgcn_exp2f(p1[r]);
;     float ps = 0.f;
; #pragma unroll
;     for (int r = 0; r < 16; ++r) ps += p0[r];
; #pragma unroll
;     for (int r = 0; r < 16; ++r) ps += p1[r];
;     { auto rr = __builtin_amdgcn_permlane32_swap(__float_as_uint(ps), __float_as_uint(ps), false, false); ps = __uint_as_float(rr[0]) + __uint_as_float(rr[1]); }
;     l_reg = l_reg * alpha + ps;
;     ...
;     ATT_PK4(p0, 0, pa0); ATT_PK4(p0, 8, pa1); ATT_PK4(p1, 0, pa2); ATT_PK4(p1, 8, pa3);
; DI void attn_pass_pipe(LAS unsigned char* lds, const bf16_t* __restrict__ Zb, size_t qoff, int kcol, int vcol, int t0, int NT, f32x16 (&o)[4], float& l_out) {
;     ...
;     PP_SB(); qkt64(pB0, pB1, Kl + KBUF, qr, r32, hi);
;     finishSM(pA0, pA1, alA, l_reg, pa0, pa1, pa2, pa3); PP_SB();
;     pv128(o, vb0, pa0, pa1, pa2, pa3); partialSM(pB0, pB1, m_reg, mnB, alB);
;     __syncthreads(); PP_RESC(alB);
;     finishSM(pB0, pB1, alB, l_reg, pa0, pa1, pa2, pa3); PP_SB();
;     pv128(o, vb0 + VBUF, pa0, pa1, pa2, pa3);
;     __builtin_amdgcn_s_setprio(0);
;     __syncthreads();
.LBB0_431:
	v_cndmask_b32_e64 v96, v101, v142, s[4:5]
	v_mul_f32_e32 v96, 0xbe38aa3b, v96
	v_pk_fma_f32 v[80:81], v[80:81], s[90:91], v[96:97] op_sel_hi:[1,0,0]
	v_exp_f32_e32 v80, v80
	v_fmamk_f32 v82, v82, 0x3e38aa3b, v96
	v_exp_f32_e32 v81, v81
	v_fmamk_f32 v83, v83, 0x3e38aa3b, v96
	v_exp_f32_e32 v82, v82
	v_fmamk_f32 v95, v95, 0x3e38aa3b, v96
	v_fmamk_f32 v94, v94, 0x3e38aa3b, v96
	v_fmamk_f32 v93, v93, 0x3e38aa3b, v96
	v_fmamk_f32 v92, v92, 0x3e38aa3b, v96
	v_fmamk_f32 v91, v91, 0x3e38aa3b, v96
	v_fmamk_f32 v90, v90, 0x3e38aa3b, v96
	v_fmamk_f32 v89, v89, 0x3e38aa3b, v96
	v_fmamk_f32 v88, v88, 0x3e38aa3b, v96
	v_fmamk_f32 v87, v87, 0x3e38aa3b, v96
	v_fmamk_f32 v86, v86, 0x3e38aa3b, v96
	v_fmamk_f32 v85, v85, 0x3e38aa3b, v96
	v_fmamk_f32 v84, v84, 0x3e38aa3b, v96
	v_exp_f32_e32 v83, v83
	v_fmamk_f32 v79, v79, 0x3e38aa3b, v96
	v_fmamk_f32 v78, v78, 0x3e38aa3b, v96
	v_fmamk_f32 v77, v77, 0x3e38aa3b, v96
	v_fmamk_f32 v76, v76, 0x3e38aa3b, v96
	v_fmamk_f32 v75, v75, 0x3e38aa3b, v96
	v_fmamk_f32 v74, v74, 0x3e38aa3b, v96
	v_fmamk_f32 v73, v73, 0x3e38aa3b, v96
	v_fmamk_f32 v72, v72, 0x3e38aa3b, v96
	v_fmamk_f32 v71, v71, 0x3e38aa3b, v96
	v_fmamk_f32 v70, v70, 0x3e38aa3b, v96
	v_fmamk_f32 v69, v69, 0x3e38aa3b, v96
	v_fmamk_f32 v68, v68, 0x3e38aa3b, v96
	v_fmamk_f32 v67, v67, 0x3e38aa3b, v96
	v_fmamk_f32 v66, v66, 0x3e38aa3b, v96
	v_fmamk_f32 v65, v65, 0x3e38aa3b, v96
	v_fmac_f32_e32 v96, 0x3e38aa3b, v64
	v_exp_f32_e32 v84, v84
	v_exp_f32_e32 v64, v96
	v_exp_f32_e32 v96, v65
	v_add_f32_e32 v65, 0, v80
	v_exp_f32_e32 v85, v85
	v_add_f32_e32 v65, v81, v65
	v_exp_f32_e32 v86, v86
	v_add_f32_e32 v65, v82, v65
	v_exp_f32_e32 v87, v87
	v_add_f32_e32 v65, v83, v65
	v_exp_f32_e32 v88, v88
	v_add_f32_e32 v65, v84, v65
	v_exp_f32_e32 v89, v89
	v_add_f32_e32 v65, v85, v65
	v_exp_f32_e32 v90, v90
	v_add_f32_e32 v65, v86, v65
	v_exp_f32_e32 v91, v91
	v_add_f32_e32 v65, v87, v65
	v_exp_f32_e32 v92, v92
	v_add_f32_e32 v65, v88, v65
	v_exp_f32_e32 v93, v93
	v_add_f32_e32 v65, v89, v65
	v_exp_f32_e32 v94, v94
	v_add_f32_e32 v65, v90, v65
	v_exp_f32_e32 v95, v95
	v_add_f32_e32 v65, v91, v65
	v_add_f32_e32 v65, v92, v65
	v_add_f32_e32 v65, v93, v65
	v_exp_f32_e32 v66, v66
	v_add_f32_e32 v65, v94, v65
	v_exp_f32_e32 v101, v67
	v_add_f32_e32 v65, v95, v65
	v_exp_f32_e32 v102, v68
	v_add_f32_e32 v65, v64, v65
	v_exp_f32_e32 v103, v69
	v_add_f32_e32 v65, v96, v65
	v_exp_f32_e32 v104, v70
	v_add_f32_e32 v65, v66, v65
	v_exp_f32_e32 v105, v71
	v_add_f32_e32 v65, v101, v65
	v_exp_f32_e32 v106, v72
	v_add_f32_e32 v65, v102, v65
	v_exp_f32_e32 v107, v73
	v_add_f32_e32 v65, v103, v65
	v_exp_f32_e32 v108, v74
	v_add_f32_e32 v65, v104, v65
	v_exp_f32_e32 v109, v75
	v_add_f32_e32 v65, v105, v65
	v_exp_f32_e32 v110, v76
	v_add_f32_e32 v65, v106, v65
	v_exp_f32_e32 v111, v77
	v_add_f32_e32 v65, v107, v65
	v_exp_f32_e32 v112, v78
	v_add_f32_e32 v65, v108, v65
	v_exp_f32_e32 v113, v79
	v_add_f32_e32 v65, v109, v65
	v_add_f32_e32 v65, v110, v65
	v_add_f32_e32 v65, v111, v65
	v_add_f32_e32 v65, v112, v65
	v_add_f32_e32 v65, v113, v65
	v_mov_b32_e32 v67, v65
	v_cvt_pk_bf16_f32 v68, v80, v81
	v_cvt_pk_bf16_f32 v69, v82, v83
	v_cvt_pk_bf16_f32 v70, v84, v85
	v_cvt_pk_bf16_f32 v71, v86, v87
	s_nop 1
	v_permlane32_swap_b32_e32 v65, v67
	v_permlane32_swap_b32_e32 v68, v70
	v_permlane32_swap_b32_e32 v69, v71
	v_cvt_pk_bf16_f32 v72, v88, v89
	v_cvt_pk_bf16_f32 v73, v90, v91
	v_cvt_pk_bf16_f32 v74, v92, v93
	v_cvt_pk_bf16_f32 v75, v94, v95
	v_cvt_pk_bf16_f32 v76, v64, v96
	v_cvt_pk_bf16_f32 v77, v66, v101
	v_cvt_pk_bf16_f32 v78, v102, v103
	v_cvt_pk_bf16_f32 v79, v104, v105
	v_cvt_pk_bf16_f32 v80, v106, v107
	v_cvt_pk_bf16_f32 v81, v108, v109
	v_cvt_pk_bf16_f32 v82, v110, v111
	v_cvt_pk_bf16_f32 v83, v112, v113
	s_nop 0
	v_permlane32_swap_b32_e32 v72, v74
	v_permlane32_swap_b32_e32 v73, v75
	v_permlane32_swap_b32_e32 v76, v78
	v_permlane32_swap_b32_e32 v77, v79
	v_permlane32_swap_b32_e32 v80, v82
	v_permlane32_swap_b32_e32 v81, v83
	ds_read_b64_tr_b16 v[84:85], v177 offset:0
	ds_read_b64_tr_b16 v[86:87], v177 offset:0x800
	ds_read_b64_tr_b16 v[88:89], v177 offset:0x1000
	ds_read_b64_tr_b16 v[90:91], v177 offset:0x1800
	ds_read_b64_tr_b16 v[92:93], v177 offset:0x2000
	ds_read_b64_tr_b16 v[94:95], v177 offset:0x2800
	ds_read_b64_tr_b16 v[102:103], v177 offset:0x3000
	ds_read_b64_tr_b16 v[104:105], v177 offset:0x3800
	s_waitcnt lgkmcnt(0)
	s_nop 0
	v_mfma_f32_32x32x16_bf16 v[48:63], v[68:71], v[84:87], v[48:63]
	ds_read_b64_tr_b16 v[84:85], v177 offset:0x200
	ds_read_b64_tr_b16 v[86:87], v177 offset:0xa00
	v_mfma_f32_32x32x16_bf16 v[48:63], v[72:75], v[88:91], v[48:63]
	ds_read_b64_tr_b16 v[88:89], v177 offset:0x1200
	ds_read_b64_tr_b16 v[90:91], v177 offset:0x1a00
	v_mfma_f32_32x32x16_bf16 v[48:63], v[76:79], v[92:95], v[48:63]
	ds_read_b64_tr_b16 v[92:93], v177 offset:0x2200
	ds_read_b64_tr_b16 v[94:95], v177 offset:0x2a00
	v_mfma_f32_32x32x16_bf16 v[48:63], v[80:83], v[102:105], v[48:63]
	ds_read_b64_tr_b16 v[102:103], v177 offset:0x3200
	ds_read_b64_tr_b16 v[104:105], v177 offset:0x3a00
	s_waitcnt lgkmcnt(0)
	v_mfma_f32_32x32x16_bf16 v[32:47], v[68:71], v[84:87], v[32:47]
	ds_read_b64_tr_b16 v[84:85], v177 offset:0x400
	ds_read_b64_tr_b16 v[86:87], v177 offset:0xc00
	v_mfma_f32_32x32x16_bf16 v[32:47], v[72:75], v[88:91], v[32:47]
	ds_read_b64_tr_b16 v[88:89], v177 offset:0x1400
	ds_read_b64_tr_b16 v[90:91], v177 offset:0x1c00
	v_mfma_f32_32x32x16_bf16 v[32:47], v[76:79], v[92:95], v[32:47]
	ds_read_b64_tr_b16 v[92:93], v177 offset:0x2400
	ds_read_b64_tr_b16 v[94:95], v177 offset:0x2c00
	v_mfma_f32_32x32x16_bf16 v[32:47], v[80:83], v[102:105], v[32:47]
	ds_read_b64_tr_b16 v[102:103], v177 offset:0x3400
	ds_read_b64_tr_b16 v[104:105], v177 offset:0x3c00
	s_waitcnt lgkmcnt(0)
	v_mfma_f32_32x32x16_bf16 v[16:31], v[68:71], v[84:87], v[16:31]
	ds_read_b64_tr_b16 v[84:85], v177 offset:0x600
	ds_read_b64_tr_b16 v[86:87], v177 offset:0xe00
	v_mfma_f32_32x32x16_bf16 v[16:31], v[72:75], v[88:91], v[16:31]
	ds_read_b64_tr_b16 v[88:89], v177 offset:0x1600
	ds_read_b64_tr_b16 v[90:91], v177 offset:0x1e00
	v_mfma_f32_32x32x16_bf16 v[16:31], v[76:79], v[92:95], v[16:31]
	ds_read_b64_tr_b16 v[92:93], v177 offset:0x2600
	ds_read_b64_tr_b16 v[94:95], v177 offset:0x2e00
	v_mfma_f32_32x32x16_bf16 v[16:31], v[80:83], v[102:105], v[16:31]
	ds_read_b64_tr_b16 v[102:103], v177 offset:0x3600
	ds_read_b64_tr_b16 v[104:105], v177 offset:0x3e00
	s_waitcnt lgkmcnt(0)
	v_mfma_f32_32x32x16_bf16 v[0:15], v[68:71], v[84:87], v[0:15]
	v_mfma_f32_32x32x16_bf16 v[0:15], v[72:75], v[88:91], v[0:15]
	v_mfma_f32_32x32x16_bf16 v[0:15], v[76:79], v[92:95], v[0:15]
	v_mfma_f32_32x32x16_bf16 v[0:15], v[80:83], v[102:105], v[0:15]
	s_setprio 0
	v_mov_b32_e32 v64, v196
	s_barrier
; #define LAS __attribute__((address_space(3)))
; DI void row_rcp(LAS unsigned char* lds, float l, float (&rli)[16]) {
;     int tid_ = threadIdx.x; asm volatile("" : "+v"(tid_));
;     const int tid = tid_, wid = tid >> 6, lane = tid & 63, r32 = lane & 31, hi = lane >> 5;
;     LAS float* wsf = (LAS float*)(lds + L_WS) + wid * 64;
;     if (hi == 0) wsf[32 + r32] = l;
	s_nop 0
	v_bfe_u32 v68, v64, 5, 1
	v_and_b32_e32 v66, 0x3fffffc0, v64
	v_lshl_add_u32 v69, v66, 2, 0
	v_cmp_eq_u32_e32 vcc, 0, v68
	s_and_saveexec_b64 s[0:1], vcc
	s_cbranch_execz .LBB0_390
	v_and_b32_e32 v64, 31, v64
	v_lshl_add_u32 v70, v64, 2, v69
	v_mul_f32_e32 v64, v176, v143
	v_add_f32_e32 v66, v98, v99
	v_pk_add_f32 v[64:65], v[64:65], v[66:67]
	s_nop 0
	v_fmac_f32_e32 v65, v64, v100
	ds_write_b32 v70, v65 offset:51328
	s_branch .LBB0_390

; #define LAS __attribute__((address_space(3)))
; DI void partialSM(f32x16& p0, f32x16& p1, float& m_reg, float& mn, float& alpha) {
;     ...
;     else { mn = fmaxf(m_reg, pmax); alpha = __builtin_amdgcn_exp2f((m_reg - mn) * CL2); m_reg = mn; }
;     const float mnC = -mn * CL2;
; #pragma unroll
;     for (int r = 0; r < 16; ++r) p0[r] = fmaf(p0[r], CL2, mnC);
; #pragma unroll
;     for (int r = 0; r < 16; ++r) p1[r] = fmaf(p1[r], CL2, mnC);
; #pragma unroll
;     for (int r = 0; r < 16; ++r) p0[r] = __builtin_amdgcn_exp2f(p0[r]);
; }
; DI void finishSM(f32x16& p0, f32x16& p1, float alpha, float& l_reg, bf16x8& pa0, bf16x8& pa1, bf16x8& pa2, bf16x8& pa3) {
; #pragma unroll
;     for (int r = 0; r < 16; ++r) p1[r] = __builtin_amdgcn_exp2f(p1[r]);
;     float ps = 0.f;
; #pragma unroll
;     for (int r = 0; r < 16; ++r) ps += p0[r];
; #pragma unroll
;     for (int r = 0; r < 16; ++r) ps += p1[r];
;     { auto rr = __builtin_amdgcn_permlane32_swap(__float_as_uint(ps), __float_as_uint(ps), false, false); ps = __uint_as_float(rr[0]) + __uint_as_float(rr[1]); }
;     l_reg = l_reg * alpha + ps;
;     ...
;     ATT_PK4(p0, 0, pa0); ATT_PK4(p0, 8, pa1); ATT_PK4(p1, 0, pa2); ATT_PK4(p1, 8, pa3);
;     ...
; }
; DI void qkt64(f32x16& p0, f32x16& p1, const LAS unsigned char* Kb, const bf16x8 (&qr)[4], int r32, int hi) {
; #pragma unroll
;     for (int r = 0; r < 16; ++r) { p0[r] = 0.f; p1[r] = 0.f; }
; #pragma unroll
;     for (int d0 = 0; d0 < 4; ++d0) { const int cb = d0 * 32 + hi * 16;
;         const bf16x8 b0 = *(const LAS bf16x8*)(Kb + r32 * KROWB + cb), b1 = *(const LAS bf16x8*)(Kb + (32 + r32) * KROWB + cb);
;         p0 = __builtin_amdgcn_mfma_f32_32x32x16_bf16(b0, qr[d0], p0, 0, 0, 0);
;         p1 = __builtin_amdgcn_mfma_f32_32x32x16_bf16(b1, qr[d0], p1, 0, 0, 0); }
.LBB0_475:
	v_cndmask_b32_e64 v184, v138, v142, s[8:9]
	v_mul_f32_e32 v185, 0xbe38aa3b, v184
	v_pk_fma_f32 v[80:81], v[80:81], s[90:91], v[184:185] op_sel:[0,0,1] op_sel_hi:[1,0,1]
	v_pk_fma_f32 v[82:83], v[82:83], s[90:91], v[184:185] op_sel:[0,0,1] op_sel_hi:[1,0,1]
	v_pk_fma_f32 v[84:85], v[84:85], s[90:91], v[184:185] op_sel:[0,0,1] op_sel_hi:[1,0,1]
	v_pk_fma_f32 v[86:87], v[86:87], s[90:91], v[184:185] op_sel:[0,0,1] op_sel_hi:[1,0,1]
	v_pk_fma_f32 v[88:89], v[88:89], s[90:91], v[184:185] op_sel:[0,0,1] op_sel_hi:[1,0,1]
	v_pk_fma_f32 v[90:91], v[90:91], s[90:91], v[184:185] op_sel:[0,0,1] op_sel_hi:[1,0,1]
	v_pk_fma_f32 v[92:93], v[92:93], s[90:91], v[184:185] op_sel:[0,0,1] op_sel_hi:[1,0,1]
	v_pk_fma_f32 v[94:95], v[94:95], s[90:91], v[184:185] op_sel:[0,0,1] op_sel_hi:[1,0,1]
	v_exp_f32_e32 v138, v80
	v_exp_f32_e32 v153, v81
	v_exp_f32_e32 v139, v82
	v_exp_f32_e32 v152, v83
	v_exp_f32_e32 v140, v84
	v_exp_f32_e32 v151, v85
	v_exp_f32_e32 v141, v86
	v_exp_f32_e32 v150, v87
	v_exp_f32_e32 v142, v88
	v_exp_f32_e32 v149, v89
	v_exp_f32_e32 v143, v90
	v_exp_f32_e32 v148, v91
	v_exp_f32_e32 v144, v92
	v_exp_f32_e32 v147, v93
	v_exp_f32_e32 v145, v94
	v_exp_f32_e32 v146, v95
	v_fmamk_f32 v194, v64, 0x3e38aa3b, v185
	v_fmamk_f32 v195, v65, 0x3e38aa3b, v185
	v_fmamk_f32 v202, v66, 0x3e38aa3b, v185
	v_fmamk_f32 v203, v67, 0x3e38aa3b, v185
	v_fmamk_f32 v204, v68, 0x3e38aa3b, v185
	v_fmamk_f32 v187, v69, 0x3e38aa3b, v185
	v_fmamk_f32 v188, v70, 0x3e38aa3b, v185
	v_fmamk_f32 v189, v71, 0x3e38aa3b, v185
	v_fmamk_f32 v190, v72, 0x3e38aa3b, v185
	v_fmamk_f32 v191, v73, 0x3e38aa3b, v185
	v_fmamk_f32 v192, v74, 0x3e38aa3b, v185
	v_fmamk_f32 v193, v75, 0x3e38aa3b, v185
	v_fmamk_f32 v186, v76, 0x3e38aa3b, v185
	v_fmamk_f32 v205, v77, 0x3e38aa3b, v185
	v_fmamk_f32 v206, v78, 0x3e38aa3b, v185
	v_fmac_f32_e32 v185, 0x3e38aa3b, v79
	s_waitcnt lgkmcnt(0)
	s_barrier
	ds_read_b128 v[64:67], v178 offset:4608
	ds_read_b128 v[68:71], v178
	ds_read_b128 v[208:211], v178 offset:32
	ds_read_b128 v[212:215], v178 offset:4640
	v_exp_f32_e32 v194, v194
	v_exp_f32_e32 v195, v195
	s_waitcnt lgkmcnt(2)
	v_mfma_f32_32x32x16_bf16 v[80:95], v[68:71], v[110:113], 0
	v_exp_f32_e32 v202, v202
	v_exp_f32_e32 v203, v203
	v_exp_f32_e32 v204, v204
	v_exp_f32_e32 v187, v187
	v_exp_f32_e32 v188, v188
	v_exp_f32_e32 v189, v189
	v_exp_f32_e32 v190, v190
	v_mfma_f32_32x32x16_bf16 v[64:79], v[64:67], v[110:113], 0
	v_exp_f32_e32 v191, v191
	v_exp_f32_e32 v192, v192
	v_exp_f32_e32 v193, v193
	v_exp_f32_e32 v207, v186
	v_exp_f32_e32 v205, v205
	v_exp_f32_e32 v206, v206
	s_waitcnt lgkmcnt(1)
	v_mfma_f32_32x32x16_bf16 v[80:95], v[208:211], v[106:109], v[80:95]
	s_waitcnt lgkmcnt(0)
	v_mfma_f32_32x32x16_bf16 v[64:79], v[212:215], v[106:109], v[64:79]
	ds_read_b128 v[208:211], v178 offset:64
	ds_read_b128 v[212:215], v178 offset:4672
	s_waitcnt lgkmcnt(1)
	v_mfma_f32_32x32x16_bf16 v[80:95], v[208:211], v[102:105], v[80:95]
	s_waitcnt lgkmcnt(0)
	v_mfma_f32_32x32x16_bf16 v[64:79], v[212:215], v[102:105], v[64:79]
	ds_read_b128 v[208:211], v178 offset:96
	ds_read_b128 v[212:215], v178 offset:4704
	s_waitcnt lgkmcnt(1)
	v_mfma_f32_32x32x16_bf16 v[80:95], v[208:211], v[98:101], v[80:95]
	v_exp_f32_e32 v208, v185
	v_add_f32_e32 v185, 0, v138
	v_add_f32_e32 v185, v153, v185
	v_add_f32_e32 v185, v139, v185
	v_add_f32_e32 v185, v152, v185
	v_add_f32_e32 v185, v140, v185
	v_add_f32_e32 v185, v151, v185
	v_add_f32_e32 v185, v141, v185
	v_add_f32_e32 v185, v150, v185
	v_add_f32_e32 v185, v142, v185
	v_add_f32_e32 v185, v149, v185
	v_add_f32_e32 v185, v143, v185
	v_add_f32_e32 v185, v148, v185
	v_add_f32_e32 v185, v144, v185
	v_add_f32_e32 v185, v147, v185
	v_add_f32_e32 v185, v145, v185
	v_add_f32_e32 v185, v146, v185
	v_add_f32_e32 v185, v194, v185
	v_add_f32_e32 v185, v195, v185
	v_add_f32_e32 v185, v202, v185
	v_add_f32_e32 v185, v203, v185
	v_add_f32_e32 v185, v204, v185
	v_add_f32_e32 v185, v187, v185
	v_add_f32_e32 v185, v188, v185
	v_add_f32_e32 v185, v189, v185
	v_add_f32_e32 v185, v190, v185
	v_add_f32_e32 v185, v191, v185
	s_waitcnt lgkmcnt(0)
	v_mfma_f32_32x32x16_bf16 v[64:79], v[212:215], v[98:101], v[64:79]
	v_add_f32_e32 v185, v192, v185
	v_add_f32_e32 v185, v193, v185
	v_add_f32_e32 v185, v207, v185
	v_add_f32_e32 v185, v205, v185
	v_add_f32_e32 v185, v206, v185
	v_add_f32_e32 v185, v208, v185
	v_mov_b32_e32 v186, v185
	v_cvt_pk_bf16_f32 v138, v138, v153
	v_cvt_pk_bf16_f32 v139, v139, v152
	v_cvt_pk_bf16_f32 v140, v140, v151
	v_cvt_pk_bf16_f32 v141, v141, v150
	v_cvt_pk_bf16_f32 v142, v142, v149
	v_cvt_pk_bf16_f32 v143, v143, v148
	v_cvt_pk_bf16_f32 v144, v144, v147
	v_cvt_pk_bf16_f32 v145, v145, v146
	v_cvt_pk_bf16_f32 v146, v194, v195
	v_cvt_pk_bf16_f32 v147, v202, v203
	v_cvt_pk_bf16_f32 v148, v204, v187
	v_cvt_pk_bf16_f32 v149, v188, v189
	v_cvt_pk_bf16_f32 v150, v190, v191
	v_cvt_pk_bf16_f32 v151, v192, v193
	v_cvt_pk_bf16_f32 v152, v207, v205
	v_cvt_pk_bf16_f32 v153, v206, v208
	s_nop 1
	v_permlane32_swap_b32_e32 v185, v186
	v_permlane32_swap_b32_e32 v138, v140
	v_permlane32_swap_b32_e32 v139, v141
	v_permlane32_swap_b32_e32 v142, v144
	v_permlane32_swap_b32_e32 v143, v145
	v_permlane32_swap_b32_e32 v146, v148
	v_permlane32_swap_b32_e32 v147, v149
	v_permlane32_swap_b32_e32 v150, v152
	v_permlane32_swap_b32_e32 v151, v153
	s_cmp_ge_u32 s48, s54
	s_cbranch_scc1 .LBB0_477
	v_add_co_u32_e32 v114, vcc, 0xc4e0000, v168
	s_nop 1
	v_addc_co_u32_e32 v115, vcc, 0, v169, vcc
	v_add_co_u32_e32 v118, vcc, 0xc4e0000, v166
	global_load_dwordx4 v[114:117], v[114:115], off offset:1024
	s_nop 0
	v_addc_co_u32_e32 v119, vcc, 0, v167, vcc
	v_add_co_u32_e32 v122, vcc, 0xc53c000, v166
	s_nop 1
	v_addc_co_u32_e32 v123, vcc, 0, v167, vcc
	global_load_dwordx4 v[118:121], v[118:119], off offset:2048
	s_nop 0
	global_load_dwordx4 v[122:125], v[122:123], off offset:2048

; #define PP_WRITEO() do { *(LAS bf16x8*)(Kl + KBUF + kl) = ksO; *(LAS bf16x8*)(Vl + VBUF + vl0) = v0O; *(LAS bf16x8*)(Vl + VBUF + vl1) = v1O; } while (0)
; #define PP_RESC(a) do { if (__any((a) < 1.f)) { if (hi == 0) wsf[r32] = (a); asm volatile("s_waitcnt lgkmcnt(0)" ::: "memory"); \
;     _Pragma("unroll") for (int r = 0; r < 16; ++r) { const float a_ = wsf[crow(r, hi)]; _Pragma("unroll") for (int d = 0; d < 4; ++d) o[d][r] *= a_; } } } while (0)
; DI void partialSM(f32x16& p0, f32x16& p1, float& m_reg, float& mn, float& alpha) {
;     ...
;     if (__builtin_expect(__all(pmax - m_reg <= THRS), 1)) { mn = m_reg; alpha = 1.f; }
;     else { mn = fmaxf(m_reg, pmax); alpha = __builtin_amdgcn_exp2f((m_reg - mn) * CL2); m_reg = mn; }
;     const float mnC = -mn * CL2;
; #pragma unroll
;     for (int r = 0; r < 16; ++r) p0[r] = fmaf(p0[r], CL2, mnC);
; #pragma unroll
;     for (int r = 0; r < 16; ++r) p1[r] = fmaf(p1[r], CL2, mnC);
; #pragma unroll
;     for (int r = 0; r < 16; ++r) p0[r] = __builtin_amdgcn_exp2f(p0[r]);
; DI void attn_pass_pipe(LAS unsigned char* lds, const bf16_t* __restrict__ Zb, size_t qoff, int kcol, int vcol, int t0, int NT, f32x16 (&o)[4], float& l_out) {
;     ...
;         pv128(o, vb0 + VBUF, pa0, pa1, pa2, pa3); partialSM(pA0, pA1, m_reg, mnA, alA);
;         __syncthreads(); PP_WRITEO();
;         PP_RESC(alA); __syncthreads();
;     }
.LBB0_481:
	v_cndmask_b32_e64 v142, v138, v184, s[8:9]
	v_mul_f32_e32 v126, 0xbe38aa3b, v142
	v_mov_b32_e32 v127, v126
	v_pk_fma_f32 v[80:81], v[80:81], s[90:91], v[126:127] op_sel_hi:[1,0,0]
	v_pk_fma_f32 v[82:83], v[82:83], s[90:91], v[126:127] op_sel_hi:[1,0,0]
	v_pk_fma_f32 v[84:85], v[84:85], s[90:91], v[126:127] op_sel_hi:[1,0,0]
	v_pk_fma_f32 v[86:87], v[86:87], s[90:91], v[126:127] op_sel_hi:[1,0,0]
	v_pk_fma_f32 v[88:89], v[88:89], s[90:91], v[126:127] op_sel_hi:[1,0,0]
	v_pk_fma_f32 v[90:91], v[90:91], s[90:91], v[126:127] op_sel_hi:[1,0,0]
	v_pk_fma_f32 v[92:93], v[92:93], s[90:91], v[126:127] op_sel_hi:[1,0,0]
	v_fmamk_f32 v94, v94, 0x3e38aa3b, v126
	v_fmac_f32_e32 v127, 0x3e38aa3b, v95
	v_exp_f32_e32 v152, v80
	v_exp_f32_e32 v168, v81
	v_exp_f32_e32 v153, v82
	v_exp_f32_e32 v169, v83
	v_exp_f32_e32 v166, v84
	v_exp_f32_e32 v184, v85
	v_exp_f32_e32 v167, v86
	v_exp_f32_e32 v187, v87
	v_exp_f32_e32 v144, v88
	v_exp_f32_e32 v148, v89
	v_exp_f32_e32 v145, v90
	v_exp_f32_e32 v149, v91
	v_exp_f32_e32 v146, v92
	v_exp_f32_e32 v150, v93
	v_exp_f32_e32 v147, v94
	v_exp_f32_e32 v151, v127
	v_pk_fma_f32 v[138:139], v[64:65], s[90:91], v[126:127] op_sel_hi:[1,0,0]
	v_add_f32_e32 v64, v181, v182
	v_fmac_f32_e32 v64, v180, v173
	v_add_f32_e32 v173, v185, v186
	s_add_i32 s0, s48, 2
	s_add_i32 s1, s48, -1
	v_pk_fma_f32 v[136:137], v[66:67], s[90:91], v[126:127] op_sel_hi:[1,0,0]
	v_pk_fma_f32 v[134:135], v[68:69], s[90:91], v[126:127] op_sel_hi:[1,0,0]
	v_pk_fma_f32 v[130:131], v[70:71], s[90:91], v[126:127] op_sel_hi:[1,0,0]
	v_pk_fma_f32 v[128:129], v[72:73], s[90:91], v[126:127] op_sel_hi:[1,0,0]
	v_pk_fma_f32 v[140:141], v[74:75], s[90:91], v[126:127] op_sel_hi:[1,0,0]
	v_pk_fma_f32 v[132:133], v[76:77], s[90:91], v[126:127] op_sel_hi:[1,0,0]
	v_pk_fma_f32 v[126:127], v[78:79], s[90:91], v[126:127] op_sel_hi:[1,0,0]
	v_fmac_f32_e32 v173, v64, v183
	v_lshl_add_u64 v[158:159], v[158:159], 0, s[92:93]
	s_cmp_ge_u32 s1, s82
	v_lshl_add_u64 v[162:163], v[162:163], 0, s[92:93]
	s_waitcnt lgkmcnt(0)
	s_barrier
	s_cbranch_scc1 .LBB0_496
	s_mov_b32 s48, s0
	v_mov_b32_e32 v180, v143
	s_branch .LBB0_471

; #define PP_RESC(a) do { if (__any((a) < 1.f)) { if (hi == 0) wsf[r32] = (a); asm volatile("s_waitcnt lgkmcnt(0)" ::: "memory"); \
;     _Pragma("unroll") for (int r = 0; r < 16; ++r) { const float a_ = wsf[crow(r, hi)]; _Pragma("unroll") for (int d = 0; d < 4; ++d) o[d][r] *= a_; } } } while (0)
; #define PP_SB() __builtin_amdgcn_sched_barrier(0)
; DI void partialSM(f32x16& p0, f32x16& p1, float& m_reg, float& mn, float& alpha) {
;     ...
;     const float mnC = -mn * CL2;
; #pragma unroll
;     for (int r = 0; r < 16; ++r) p0[r] = fmaf(p0[r], CL2, mnC);
; #pragma unroll
;     for (int r = 0; r < 16; ++r) p1[r] = fmaf(p1[r], CL2, mnC);
; #pragma unroll
;     for (int r = 0; r < 16; ++r) p0[r] = __builtin_amdgcn_exp2f(p0[r]);
; }
; DI void finishSM(f32x16& p0, f32x16& p1, float alpha, float& l_reg, bf16x8& pa0, bf16x8& pa1, bf16x8& pa2, bf16x8& pa3) {
; #pragma unroll
;     for (int r = 0; r < 16; ++r) p1[r] = __builtin_amdgcn_exp2f(p1[r]);
;     float ps = 0.f;
; #pragma unroll
;     for (int r = 0; r < 16; ++r) ps += p0[r];
; #pragma unroll
;     for (int r = 0; r < 16; ++r) ps += p1[r];
;     { auto rr = __builtin_amdgcn_permlane32_swap(__float_as_uint(ps), __float_as_uint(ps), false, false); ps = __uint_as_float(rr[0]) + __uint_as_float(rr[1]); }
;     l_reg = l_reg * alpha + ps;
;     ...
;     ATT_PK4(p0, 0, pa0); ATT_PK4(p0, 8, pa1); ATT_PK4(p1, 0, pa2); ATT_PK4(p1, 8, pa3);
; DI void attn_pass_pipe(LAS unsigned char* lds, const bf16_t* __restrict__ Zb, size_t qoff, int kcol, int vcol, int t0, int NT, f32x16 (&o)[4], float& l_out) {
;     ...
;     PP_SB(); qkt64(pB0, pB1, Kl + KBUF, qr, r32, hi);
;     finishSM(pA0, pA1, alA, l_reg, pa0, pa1, pa2, pa3); PP_SB();
;     pv128(o, vb0, pa0, pa1, pa2, pa3); partialSM(pB0, pB1, m_reg, mnB, alB);
;     __syncthreads(); PP_RESC(alB);
;     finishSM(pB0, pB1, alB, l_reg, pa0, pa1, pa2, pa3); PP_SB();
;     pv128(o, vb0 + VBUF, pa0, pa1, pa2, pa3);
;     __builtin_amdgcn_s_setprio(0);
;     __syncthreads();
.LBB0_500:
	v_cndmask_b32_e64 v96, v101, v142, s[8:9]
	v_mul_f32_e32 v96, 0xbe38aa3b, v96
	v_pk_fma_f32 v[80:81], v[80:81], s[90:91], v[96:97] op_sel_hi:[1,0,0]
	v_exp_f32_e32 v80, v80
	v_fmamk_f32 v82, v82, 0x3e38aa3b, v96
	v_exp_f32_e32 v81, v81
	v_fmamk_f32 v83, v83, 0x3e38aa3b, v96
	v_exp_f32_e32 v82, v82
	v_fmamk_f32 v95, v95, 0x3e38aa3b, v96
	v_fmamk_f32 v94, v94, 0x3e38aa3b, v96
	v_fmamk_f32 v93, v93, 0x3e38aa3b, v96
	v_fmamk_f32 v92, v92, 0x3e38aa3b, v96
	v_fmamk_f32 v91, v91, 0x3e38aa3b, v96
	v_fmamk_f32 v90, v90, 0x3e38aa3b, v96
	v_fmamk_f32 v89, v89, 0x3e38aa3b, v96
	v_fmamk_f32 v88, v88, 0x3e38aa3b, v96
	v_fmamk_f32 v87, v87, 0x3e38aa3b, v96
	v_fmamk_f32 v86, v86, 0x3e38aa3b, v96
	v_fmamk_f32 v85, v85, 0x3e38aa3b, v96
	v_fmamk_f32 v84, v84, 0x3e38aa3b, v96
	v_exp_f32_e32 v83, v83
	v_fmamk_f32 v79, v79, 0x3e38aa3b, v96
	v_fmamk_f32 v78, v78, 0x3e38aa3b, v96
	v_fmamk_f32 v77, v77, 0x3e38aa3b, v96
	v_fmamk_f32 v76, v76, 0x3e38aa3b, v96
	v_fmamk_f32 v75, v75, 0x3e38aa3b, v96
	v_fmamk_f32 v74, v74, 0x3e38aa3b, v96
	v_fmamk_f32 v73, v73, 0x3e38aa3b, v96
	v_fmamk_f32 v72, v72, 0x3e38aa3b, v96
	v_fmamk_f32 v71, v71, 0x3e38aa3b, v96
	v_fmamk_f32 v70, v70, 0x3e38aa3b, v96
	v_fmamk_f32 v69, v69, 0x3e38aa3b, v96
	v_fmamk_f32 v68, v68, 0x3e38aa3b, v96
	v_fmamk_f32 v67, v67, 0x3e38aa3b, v96
	v_fmamk_f32 v66, v66, 0x3e38aa3b, v96
	v_fmamk_f32 v65, v65, 0x3e38aa3b, v96
	v_fmac_f32_e32 v96, 0x3e38aa3b, v64
	v_exp_f32_e32 v84, v84
	v_exp_f32_e32 v64, v96
	v_exp_f32_e32 v96, v65
	v_add_f32_e32 v65, 0, v80
	v_exp_f32_e32 v85, v85
	v_add_f32_e32 v65, v81, v65
	v_exp_f32_e32 v86, v86
	v_add_f32_e32 v65, v82, v65
	v_exp_f32_e32 v87, v87
	v_add_f32_e32 v65, v83, v65
	v_exp_f32_e32 v88, v88
	v_add_f32_e32 v65, v84, v65
	v_exp_f32_e32 v89, v89
	v_add_f32_e32 v65, v85, v65
	v_exp_f32_e32 v90, v90
	v_add_f32_e32 v65, v86, v65
	v_exp_f32_e32 v91, v91
	v_add_f32_e32 v65, v87, v65
	v_exp_f32_e32 v92, v92
	v_add_f32_e32 v65, v88, v65
	v_exp_f32_e32 v93, v93
	v_add_f32_e32 v65, v89, v65
	v_exp_f32_e32 v94, v94
	v_add_f32_e32 v65, v90, v65
	v_exp_f32_e32 v95, v95
	v_add_f32_e32 v65, v91, v65
	v_add_f32_e32 v65, v92, v65
	v_add_f32_e32 v65, v93, v65
	v_exp_f32_e32 v66, v66
	v_add_f32_e32 v65, v94, v65
	v_exp_f32_e32 v101, v67
	v_add_f32_e32 v65, v95, v65
	v_exp_f32_e32 v102, v68
	v_add_f32_e32 v65, v64, v65
	v_exp_f32_e32 v103, v69
	v_add_f32_e32 v65, v96, v65
	v_exp_f32_e32 v104, v70
	v_add_f32_e32 v65, v66, v65
	v_exp_f32_e32 v105, v71
	v_add_f32_e32 v65, v101, v65
	v_exp_f32_e32 v106, v72
	v_add_f32_e32 v65, v102, v65
	v_exp_f32_e32 v107, v73
	v_add_f32_e32 v65, v103, v65
	v_exp_f32_e32 v108, v74
	v_add_f32_e32 v65, v104, v65
	v_exp_f32_e32 v109, v75
	v_add_f32_e32 v65, v105, v65
	v_exp_f32_e32 v110, v76
	v_add_f32_e32 v65, v106, v65
	v_exp_f32_e32 v111, v77
	v_add_f32_e32 v65, v107, v65
	v_exp_f32_e32 v112, v78
	v_add_f32_e32 v65, v108, v65
	v_exp_f32_e32 v113, v79
	v_add_f32_e32 v65, v109, v65
	v_add_f32_e32 v65, v110, v65
	v_add_f32_e32 v65, v111, v65
	v_add_f32_e32 v65, v112, v65
	v_add_f32_e32 v65, v113, v65
	v_mov_b32_e32 v67, v65
	v_cvt_pk_bf16_f32 v68, v80, v81
	v_cvt_pk_bf16_f32 v69, v82, v83
	v_cvt_pk_bf16_f32 v70, v84, v85
	v_cvt_pk_bf16_f32 v71, v86, v87
	s_nop 1
	v_permlane32_swap_b32_e32 v65, v67
	v_permlane32_swap_b32_e32 v68, v70
	v_permlane32_swap_b32_e32 v69, v71
	v_cvt_pk_bf16_f32 v72, v88, v89
	v_cvt_pk_bf16_f32 v73, v90, v91
	v_cvt_pk_bf16_f32 v74, v92, v93
	v_cvt_pk_bf16_f32 v75, v94, v95
	v_cvt_pk_bf16_f32 v76, v64, v96
	v_cvt_pk_bf16_f32 v77, v66, v101
	v_cvt_pk_bf16_f32 v78, v102, v103
	v_cvt_pk_bf16_f32 v79, v104, v105
	v_cvt_pk_bf16_f32 v80, v106, v107
	v_cvt_pk_bf16_f32 v81, v108, v109
	v_cvt_pk_bf16_f32 v82, v110, v111
	v_cvt_pk_bf16_f32 v83, v112, v113
	s_nop 0
	v_permlane32_swap_b32_e32 v72, v74
	v_permlane32_swap_b32_e32 v73, v75
	v_permlane32_swap_b32_e32 v76, v78
	v_permlane32_swap_b32_e32 v77, v79
	v_permlane32_swap_b32_e32 v80, v82
	v_permlane32_swap_b32_e32 v81, v83
	ds_read_b64_tr_b16 v[84:85], v174 offset:0
	ds_read_b64_tr_b16 v[86:87], v174 offset:0x800
	ds_read_b64_tr_b16 v[88:89], v174 offset:0x1000
	ds_read_b64_tr_b16 v[90:91], v174 offset:0x1800
	ds_read_b64_tr_b16 v[92:93], v174 offset:0x2000
	ds_read_b64_tr_b16 v[94:95], v174 offset:0x2800
	ds_read_b64_tr_b16 v[102:103], v174 offset:0x3000
	ds_read_b64_tr_b16 v[104:105], v174 offset:0x3800
	s_waitcnt lgkmcnt(0)
	s_nop 0
	v_mfma_f32_32x32x16_bf16 v[48:63], v[68:71], v[84:87], v[48:63]
	ds_read_b64_tr_b16 v[84:85], v174 offset:0x200
	ds_read_b64_tr_b16 v[86:87], v174 offset:0xa00
	v_mfma_f32_32x32x16_bf16 v[48:63], v[72:75], v[88:91], v[48:63]
	ds_read_b64_tr_b16 v[88:89], v174 offset:0x1200
	ds_read_b64_tr_b16 v[90:91], v174 offset:0x1a00
	v_mfma_f32_32x32x16_bf16 v[48:63], v[76:79], v[92:95], v[48:63]
	ds_read_b64_tr_b16 v[92:93], v174 offset:0x2200
	ds_read_b64_tr_b16 v[94:95], v174 offset:0x2a00
	v_mfma_f32_32x32x16_bf16 v[48:63], v[80:83], v[102:105], v[48:63]
	ds_read_b64_tr_b16 v[102:103], v174 offset:0x3200
	ds_read_b64_tr_b16 v[104:105], v174 offset:0x3a00
	s_waitcnt lgkmcnt(0)
	v_mfma_f32_32x32x16_bf16 v[32:47], v[68:71], v[84:87], v[32:47]
	ds_read_b64_tr_b16 v[84:85], v174 offset:0x400
	ds_read_b64_tr_b16 v[86:87], v174 offset:0xc00
	v_mfma_f32_32x32x16_bf16 v[32:47], v[72:75], v[88:91], v[32:47]
	ds_read_b64_tr_b16 v[88:89], v174 offset:0x1400
	ds_read_b64_tr_b16 v[90:91], v174 offset:0x1c00
	v_mfma_f32_32x32x16_bf16 v[32:47], v[76:79], v[92:95], v[32:47]
	ds_read_b64_tr_b16 v[92:93], v174 offset:0x2400
	ds_read_b64_tr_b16 v[94:95], v174 offset:0x2c00
	v_mfma_f32_32x32x16_bf16 v[32:47], v[80:83], v[102:105], v[32:47]
	ds_read_b64_tr_b16 v[102:103], v174 offset:0x3400
	ds_read_b64_tr_b16 v[104:105], v174 offset:0x3c00
	s_waitcnt lgkmcnt(0)
	v_mfma_f32_32x32x16_bf16 v[16:31], v[68:71], v[84:87], v[16:31]
	ds_read_b64_tr_b16 v[84:85], v174 offset:0x600
	ds_read_b64_tr_b16 v[86:87], v174 offset:0xe00
	v_mfma_f32_32x32x16_bf16 v[16:31], v[72:75], v[88:91], v[16:31]
	ds_read_b64_tr_b16 v[88:89], v174 offset:0x1600
	ds_read_b64_tr_b16 v[90:91], v174 offset:0x1e00
	v_mfma_f32_32x32x16_bf16 v[16:31], v[76:79], v[92:95], v[16:31]
	ds_read_b64_tr_b16 v[92:93], v174 offset:0x2600
	ds_read_b64_tr_b16 v[94:95], v174 offset:0x2e00
	v_mfma_f32_32x32x16_bf16 v[16:31], v[80:83], v[102:105], v[16:31]
	ds_read_b64_tr_b16 v[102:103], v174 offset:0x3600
	ds_read_b64_tr_b16 v[104:105], v174 offset:0x3e00
	s_waitcnt lgkmcnt(0)
	v_mfma_f32_32x32x16_bf16 v[0:15], v[68:71], v[84:87], v[0:15]
	v_mfma_f32_32x32x16_bf16 v[0:15], v[72:75], v[88:91], v[0:15]
	v_mfma_f32_32x32x16_bf16 v[0:15], v[76:79], v[92:95], v[0:15]
	v_mfma_f32_32x32x16_bf16 v[0:15], v[80:83], v[102:105], v[0:15]
	s_setprio 0
	v_mov_b32_e32 v64, v196
	s_barrier
; #define LAS __attribute__((address_space(3)))
; DI void row_rcp(LAS unsigned char* lds, float l, float (&rli)[16]) {
;     int tid_ = threadIdx.x; asm volatile("" : "+v"(tid_));
;     const int tid = tid_, wid = tid >> 6, lane = tid & 63, r32 = lane & 31, hi = lane >> 5;
;     LAS float* wsf = (LAS float*)(lds + L_WS) + wid * 64;
;     if (hi == 0) wsf[32 + r32] = l;
	s_nop 0
	v_bfe_u32 v68, v64, 5, 1
	v_and_b32_e32 v66, 0x3fffffc0, v64
	v_lshl_add_u32 v69, v66, 2, 0
	v_cmp_eq_u32_e32 vcc, 0, v68
	s_and_saveexec_b64 s[0:1], vcc
	s_cbranch_execz .LBB0_502
	v_and_b32_e32 v64, 31, v64
	v_lshl_add_u32 v70, v64, 2, v69
	v_mul_f32_e32 v64, v173, v143
	v_add_f32_e32 v66, v98, v99
	v_pk_add_f32 v[64:65], v[64:65], v[66:67]
	s_nop 0
	v_fmac_f32_e32 v65, v64, v100
	ds_write_b32 v70, v65 offset:51328

; #define LAS __attribute__((address_space(3)))
; DI void partialSM(f32x16& p0, f32x16& p1, float& m_reg, float& mn, float& alpha) {
;     ...
;     else { mn = fmaxf(m_reg, pmax); alpha = __builtin_amdgcn_exp2f((m_reg - mn) * CL2); m_reg = mn; }
;     const float mnC = -mn * CL2;
; #pragma unroll
;     for (int r = 0; r < 16; ++r) p0[r] = fmaf(p0[r], CL2, mnC);
; #pragma unroll
;     for (int r = 0; r < 16; ++r) p1[r] = fmaf(p1[r], CL2, mnC);
; #pragma unroll
;     for (int r = 0; r < 16; ++r) p0[r] = __builtin_amdgcn_exp2f(p0[r]);
; }
; DI void finishSM(f32x16& p0, f32x16& p1, float alpha, float& l_reg, bf16x8& pa0, bf16x8& pa1, bf16x8& pa2, bf16x8& pa3) {
; #pragma unroll
;     for (int r = 0; r < 16; ++r) p1[r] = __builtin_amdgcn_exp2f(p1[r]);
;     float ps = 0.f;
; #pragma unroll
;     for (int r = 0; r < 16; ++r) ps += p0[r];
; #pragma unroll
;     for (int r = 0; r < 16; ++r) ps += p1[r];
;     { auto rr = __builtin_amdgcn_permlane32_swap(__float_as_uint(ps), __float_as_uint(ps), false, false); ps = __uint_as_float(rr[0]) + __uint_as_float(rr[1]); }
;     l_reg = l_reg * alpha + ps;
;     ...
;     ATT_PK4(p0, 0, pa0); ATT_PK4(p0, 8, pa1); ATT_PK4(p1, 0, pa2); ATT_PK4(p1, 8, pa3);
;     ...
; }
; DI void qkt64(f32x16& p0, f32x16& p1, const LAS unsigned char* Kb, const bf16x8 (&qr)[4], int r32, int hi) {
; #pragma unroll
;     for (int r = 0; r < 16; ++r) { p0[r] = 0.f; p1[r] = 0.f; }
; #pragma unroll
;     for (int d0 = 0; d0 < 4; ++d0) { const int cb = d0 * 32 + hi * 16;
;         const bf16x8 b0 = *(const LAS bf16x8*)(Kb + r32 * KROWB + cb), b1 = *(const LAS bf16x8*)(Kb + (32 + r32) * KROWB + cb);
;         p0 = __builtin_amdgcn_mfma_f32_32x32x16_bf16(b0, qr[d0], p0, 0, 0, 0);
;         p1 = __builtin_amdgcn_mfma_f32_32x32x16_bf16(b1, qr[d0], p1, 0, 0, 0); }
.LBB0_509:
	v_cndmask_b32_e64 v187, v138, v142, s[8:9]
	v_mul_f32_e32 v188, 0xbe38aa3b, v187
	v_pk_fma_f32 v[80:81], v[80:81], s[90:91], v[188:189] op_sel_hi:[1,0,0]
	v_pk_fma_f32 v[82:83], v[82:83], s[90:91], v[188:189] op_sel_hi:[1,0,0]
	v_pk_fma_f32 v[84:85], v[84:85], s[90:91], v[188:189] op_sel_hi:[1,0,0]
	v_pk_fma_f32 v[86:87], v[86:87], s[90:91], v[188:189] op_sel_hi:[1,0,0]
	v_pk_fma_f32 v[88:89], v[88:89], s[90:91], v[188:189] op_sel_hi:[1,0,0]
	v_pk_fma_f32 v[90:91], v[90:91], s[90:91], v[188:189] op_sel_hi:[1,0,0]
	v_pk_fma_f32 v[92:93], v[92:93], s[90:91], v[188:189] op_sel_hi:[1,0,0]
	v_pk_fma_f32 v[94:95], v[94:95], s[90:91], v[188:189] op_sel_hi:[1,0,0]
	v_exp_f32_e32 v138, v80
	v_exp_f32_e32 v153, v81
	v_exp_f32_e32 v139, v82
	v_exp_f32_e32 v152, v83
	v_exp_f32_e32 v140, v84
	v_exp_f32_e32 v151, v85
	v_exp_f32_e32 v141, v86
	v_exp_f32_e32 v150, v87
	v_exp_f32_e32 v142, v88
	v_exp_f32_e32 v149, v89
	v_exp_f32_e32 v143, v90
	v_exp_f32_e32 v148, v91
	v_exp_f32_e32 v144, v92
	v_exp_f32_e32 v147, v93
	v_exp_f32_e32 v145, v94
	v_exp_f32_e32 v146, v95
	v_fmamk_f32 v203, v64, 0x3e38aa3b, v188
	v_fmamk_f32 v204, v65, 0x3e38aa3b, v188
	v_fmamk_f32 v205, v66, 0x3e38aa3b, v188
	v_fmamk_f32 v206, v67, 0x3e38aa3b, v188
	v_fmamk_f32 v207, v68, 0x3e38aa3b, v188
	v_fmamk_f32 v190, v69, 0x3e38aa3b, v188
	v_fmamk_f32 v191, v70, 0x3e38aa3b, v188
	v_fmamk_f32 v192, v71, 0x3e38aa3b, v188
	v_fmamk_f32 v193, v72, 0x3e38aa3b, v188
	v_fmamk_f32 v194, v73, 0x3e38aa3b, v188
	v_fmamk_f32 v195, v74, 0x3e38aa3b, v188
	v_fmamk_f32 v202, v75, 0x3e38aa3b, v188
	v_fmamk_f32 v189, v76, 0x3e38aa3b, v188
	v_fmamk_f32 v208, v77, 0x3e38aa3b, v188
	v_fmamk_f32 v209, v78, 0x3e38aa3b, v188
	v_fmac_f32_e32 v188, 0x3e38aa3b, v79
	s_waitcnt lgkmcnt(0)
	s_barrier
	ds_read_b128 v[64:67], v178 offset:4608
	ds_read_b128 v[68:71], v178
	ds_read_b128 v[210:213], v178 offset:32
	ds_read_b128 v[214:217], v178 offset:4640
	v_exp_f32_e32 v203, v203
	v_exp_f32_e32 v204, v204
	s_waitcnt lgkmcnt(2)
	v_mfma_f32_32x32x16_bf16 v[80:95], v[68:71], v[110:113], 0
	v_exp_f32_e32 v205, v205
	v_exp_f32_e32 v206, v206
	v_exp_f32_e32 v207, v207
	v_exp_f32_e32 v190, v190
	v_exp_f32_e32 v191, v191
	v_exp_f32_e32 v192, v192
	v_exp_f32_e32 v193, v193
	v_mfma_f32_32x32x16_bf16 v[64:79], v[64:67], v[110:113], 0
	v_exp_f32_e32 v194, v194
	v_exp_f32_e32 v195, v195
	v_exp_f32_e32 v202, v202
	v_exp_f32_e32 v208, v208
	v_exp_f32_e32 v209, v209
	s_waitcnt lgkmcnt(1)
	v_mfma_f32_32x32x16_bf16 v[80:95], v[210:213], v[106:109], v[80:95]
	s_waitcnt lgkmcnt(0)
	v_mfma_f32_32x32x16_bf16 v[64:79], v[214:217], v[106:109], v[64:79]
	ds_read_b128 v[210:213], v178 offset:64
	ds_read_b128 v[214:217], v178 offset:4672
	s_waitcnt lgkmcnt(1)
	v_mfma_f32_32x32x16_bf16 v[80:95], v[210:213], v[102:105], v[80:95]
	s_waitcnt lgkmcnt(0)
	v_mfma_f32_32x32x16_bf16 v[64:79], v[214:217], v[102:105], v[64:79]
	ds_read_b128 v[210:213], v178 offset:96
	ds_read_b128 v[214:217], v178 offset:4704
	s_waitcnt lgkmcnt(1)
	v_mfma_f32_32x32x16_bf16 v[80:95], v[210:213], v[98:101], v[80:95]
	v_exp_f32_e32 v211, v188
	v_add_f32_e32 v188, 0, v138
	v_add_f32_e32 v188, v153, v188
	v_add_f32_e32 v188, v139, v188
	v_add_f32_e32 v188, v152, v188
	v_add_f32_e32 v188, v140, v188
	v_add_f32_e32 v188, v151, v188
	v_add_f32_e32 v188, v141, v188
	v_add_f32_e32 v188, v150, v188
	v_add_f32_e32 v188, v142, v188
	v_add_f32_e32 v188, v149, v188
	v_add_f32_e32 v188, v143, v188
	v_add_f32_e32 v188, v148, v188
	v_add_f32_e32 v188, v144, v188
	v_add_f32_e32 v188, v147, v188
	v_add_f32_e32 v188, v145, v188
	v_add_f32_e32 v188, v146, v188
	v_add_f32_e32 v188, v203, v188
	v_add_f32_e32 v188, v204, v188
	v_add_f32_e32 v188, v205, v188
	v_add_f32_e32 v188, v206, v188
	v_add_f32_e32 v188, v207, v188
	v_add_f32_e32 v188, v190, v188
	v_add_f32_e32 v188, v191, v188
	v_add_f32_e32 v188, v192, v188
	v_exp_f32_e32 v210, v189
	v_add_f32_e32 v188, v193, v188
	v_add_f32_e32 v188, v194, v188
	s_waitcnt lgkmcnt(0)
	v_mfma_f32_32x32x16_bf16 v[64:79], v[214:217], v[98:101], v[64:79]
	v_add_f32_e32 v188, v195, v188
	v_add_f32_e32 v188, v202, v188
	v_add_f32_e32 v188, v210, v188
	v_add_f32_e32 v188, v208, v188
	v_add_f32_e32 v188, v209, v188
	v_add_f32_e32 v188, v211, v188
	v_mov_b32_e32 v189, v188
	v_cvt_pk_bf16_f32 v138, v138, v153
	v_cvt_pk_bf16_f32 v139, v139, v152
	v_cvt_pk_bf16_f32 v140, v140, v151
	v_cvt_pk_bf16_f32 v141, v141, v150
	v_cvt_pk_bf16_f32 v142, v142, v149
	v_cvt_pk_bf16_f32 v143, v143, v148
	v_cvt_pk_bf16_f32 v144, v144, v147
	v_cvt_pk_bf16_f32 v145, v145, v146
	v_cvt_pk_bf16_f32 v146, v203, v204
	v_cvt_pk_bf16_f32 v147, v205, v206
	v_cvt_pk_bf16_f32 v148, v207, v190
	v_cvt_pk_bf16_f32 v149, v191, v192
	v_cvt_pk_bf16_f32 v150, v193, v194
	v_cvt_pk_bf16_f32 v151, v195, v202
	v_cvt_pk_bf16_f32 v152, v210, v208
	v_cvt_pk_bf16_f32 v153, v209, v211
	s_nop 1
	v_permlane32_swap_b32_e32 v188, v189
	v_permlane32_swap_b32_e32 v138, v140
	v_permlane32_swap_b32_e32 v139, v141
	v_permlane32_swap_b32_e32 v142, v144
	v_permlane32_swap_b32_e32 v143, v145
	v_permlane32_swap_b32_e32 v146, v148
	v_permlane32_swap_b32_e32 v147, v149
	v_permlane32_swap_b32_e32 v150, v152
	v_permlane32_swap_b32_e32 v151, v153
	s_cmp_ge_u32 s48, s54
	s_cbranch_scc1 .LBB0_511
	v_add_co_u32_e32 v114, vcc, 0xc4e0000, v170
	s_nop 1
	v_addc_co_u32_e32 v115, vcc, 0, v171, vcc
	v_add_co_u32_e32 v118, vcc, 0xc4e0000, v168
	global_load_dwordx4 v[114:117], v[114:115], off offset:1152
	s_nop 0
	v_addc_co_u32_e32 v119, vcc, 0, v169, vcc
	v_add_co_u32_e32 v122, vcc, 0xc53c000, v168
	s_nop 1
	v_addc_co_u32_e32 v123, vcc, 0, v169, vcc
	global_load_dwordx4 v[118:121], v[118:119], off offset:2048
	s_nop 0
	global_load_dwordx4 v[122:125], v[122:123], off offset:2048

; #define PP_WRITEO() do { *(LAS bf16x8*)(Kl + KBUF + kl) = ksO; *(LAS bf16x8*)(Vl + VBUF + vl0) = v0O; *(LAS bf16x8*)(Vl + VBUF + vl1) = v1O; } while (0)
; #define PP_RESC(a) do { if (__any((a) < 1.f)) { if (hi == 0) wsf[r32] = (a); asm volatile("s_waitcnt lgkmcnt(0)" ::: "memory"); \
;     _Pragma("unroll") for (int r = 0; r < 16; ++r) { const float a_ = wsf[crow(r, hi)]; _Pragma("unroll") for (int d = 0; d < 4; ++d) o[d][r] *= a_; } } } while (0)
; DI void partialSM(f32x16& p0, f32x16& p1, float& m_reg, float& mn, float& alpha) {
;     ...
;     if (__builtin_expect(__all(pmax - m_reg <= THRS), 1)) { mn = m_reg; alpha = 1.f; }
;     else { mn = fmaxf(m_reg, pmax); alpha = __builtin_amdgcn_exp2f((m_reg - mn) * CL2); m_reg = mn; }
;     const float mnC = -mn * CL2;
; #pragma unroll
;     for (int r = 0; r < 16; ++r) p0[r] = fmaf(p0[r], CL2, mnC);
; #pragma unroll
;     for (int r = 0; r < 16; ++r) p1[r] = fmaf(p1[r], CL2, mnC);
; #pragma unroll
;     for (int r = 0; r < 16; ++r) p0[r] = __builtin_amdgcn_exp2f(p0[r]);
; DI void attn_pass_pipe(LAS unsigned char* lds, const bf16_t* __restrict__ Zb, size_t qoff, int kcol, int vcol, int t0, int NT, f32x16 (&o)[4], float& l_out) {
;     ...
;         pv128(o, vb0 + VBUF, pa0, pa1, pa2, pa3); partialSM(pA0, pA1, m_reg, mnA, alA);
;         __syncthreads(); PP_WRITEO();
;         PP_RESC(alA); __syncthreads();
;     }
.LBB0_515:
	v_cndmask_b32_e64 v142, v138, v187, s[8:9]
	v_mul_f32_e32 v126, 0xbe38aa3b, v142
	v_mov_b32_e32 v127, v126
	v_pk_fma_f32 v[80:81], v[80:81], s[90:91], v[126:127] op_sel_hi:[1,0,0]
	v_pk_fma_f32 v[82:83], v[82:83], s[90:91], v[126:127] op_sel_hi:[1,0,0]
	v_pk_fma_f32 v[84:85], v[84:85], s[90:91], v[126:127] op_sel_hi:[1,0,0]
	v_pk_fma_f32 v[86:87], v[86:87], s[90:91], v[126:127] op_sel_hi:[1,0,0]
	v_pk_fma_f32 v[88:89], v[88:89], s[90:91], v[126:127] op_sel_hi:[1,0,0]
	v_pk_fma_f32 v[90:91], v[90:91], s[90:91], v[126:127] op_sel_hi:[1,0,0]
	v_pk_fma_f32 v[92:93], v[92:93], s[90:91], v[126:127] op_sel_hi:[1,0,0]
	v_fmamk_f32 v94, v94, 0x3e38aa3b, v126
	v_fmac_f32_e32 v127, 0x3e38aa3b, v95
	v_exp_f32_e32 v152, v80
	v_exp_f32_e32 v170, v81
	v_exp_f32_e32 v153, v82
	v_exp_f32_e32 v171, v83
	v_exp_f32_e32 v168, v84
	v_exp_f32_e32 v187, v85
	v_exp_f32_e32 v169, v86
	v_exp_f32_e32 v190, v87
	v_exp_f32_e32 v144, v88
	v_exp_f32_e32 v148, v89
	v_exp_f32_e32 v145, v90
	v_exp_f32_e32 v149, v91
	v_exp_f32_e32 v146, v92
	v_exp_f32_e32 v150, v93
	v_exp_f32_e32 v147, v94
	v_exp_f32_e32 v151, v127
	v_pk_fma_f32 v[138:139], v[64:65], s[90:91], v[126:127] op_sel_hi:[1,0,0]
	v_add_f32_e32 v64, v184, v185
	v_fmac_f32_e32 v64, v183, v176
	v_add_f32_e32 v176, v188, v189
	s_add_i32 s0, s48, 2
	s_add_i32 s1, s48, -1
	v_pk_fma_f32 v[136:137], v[66:67], s[90:91], v[126:127] op_sel_hi:[1,0,0]
	v_pk_fma_f32 v[134:135], v[68:69], s[90:91], v[126:127] op_sel_hi:[1,0,0]
	v_pk_fma_f32 v[130:131], v[70:71], s[90:91], v[126:127] op_sel_hi:[1,0,0]
	v_pk_fma_f32 v[128:129], v[72:73], s[90:91], v[126:127] op_sel_hi:[1,0,0]
	v_pk_fma_f32 v[140:141], v[74:75], s[90:91], v[126:127] op_sel_hi:[1,0,0]
	v_pk_fma_f32 v[132:133], v[76:77], s[90:91], v[126:127] op_sel_hi:[1,0,0]
	v_pk_fma_f32 v[126:127], v[78:79], s[90:91], v[126:127] op_sel_hi:[1,0,0]
	v_fmac_f32_e32 v176, v64, v186
	v_lshl_add_u64 v[164:165], v[164:165], 0, s[92:93]
	s_cmp_ge_u32 s1, s82
	v_lshl_add_u64 v[166:167], v[166:167], 0, s[92:93]
	s_waitcnt lgkmcnt(0)
	s_barrier
	s_cbranch_scc1 .LBB0_517
	s_mov_b32 s48, s0
	v_mov_b32_e32 v183, v143
	s_branch .LBB0_505

; #define PP_RESC(a) do { if (__any((a) < 1.f)) { if (hi == 0) wsf[r32] = (a); asm volatile("s_waitcnt lgkmcnt(0)" ::: "memory"); \
;     _Pragma("unroll") for (int r = 0; r < 16; ++r) { const float a_ = wsf[crow(r, hi)]; _Pragma("unroll") for (int d = 0; d < 4; ++d) o[d][r] *= a_; } } } while (0)
; #define PP_SB() __builtin_amdgcn_sched_barrier(0)
; DI void partialSM(f32x16& p0, f32x16& p1, float& m_reg, float& mn, float& alpha) {
;     ...
;     const float mnC = -mn * CL2;
; #pragma unroll
;     for (int r = 0; r < 16; ++r) p0[r] = fmaf(p0[r], CL2, mnC);
; #pragma unroll
;     for (int r = 0; r < 16; ++r) p1[r] = fmaf(p1[r], CL2, mnC);
; #pragma unroll
;     for (int r = 0; r < 16; ++r) p0[r] = __builtin_amdgcn_exp2f(p0[r]);
; }
; DI void finishSM(f32x16& p0, f32x16& p1, float alpha, float& l_reg, bf16x8& pa0, bf16x8& pa1, bf16x8& pa2, bf16x8& pa3) {
; #pragma unroll
;     for (int r = 0; r < 16; ++r) p1[r] = __builtin_amdgcn_exp2f(p1[r]);
;     float ps = 0.f;
; #pragma unroll
;     for (int r = 0; r < 16; ++r) ps += p0[r];
; #pragma unroll
;     for (int r = 0; r < 16; ++r) ps += p1[r];
;     { auto rr = __builtin_amdgcn_permlane32_swap(__float_as_uint(ps), __float_as_uint(ps), false, false); ps = __uint_as_float(rr[0]) + __uint_as_float(rr[1]); }
;     l_reg = l_reg * alpha + ps;
;     ...
;     ATT_PK4(p0, 0, pa0); ATT_PK4(p0, 8, pa1); ATT_PK4(p1, 0, pa2); ATT_PK4(p1, 8, pa3);
; DI void attn_pass_pipe(LAS unsigned char* lds, const bf16_t* __restrict__ Zb, size_t qoff, int kcol, int vcol, int t0, int NT, f32x16 (&o)[4], float& l_out) {
;     ...
;     PP_SB(); qkt64(pB0, pB1, Kl + KBUF, qr, r32, hi);
;     finishSM(pA0, pA1, alA, l_reg, pa0, pa1, pa2, pa3); PP_SB();
;     pv128(o, vb0, pa0, pa1, pa2, pa3); partialSM(pB0, pB1, m_reg, mnB, alB);
;     __syncthreads(); PP_RESC(alB);
;     finishSM(pB0, pB1, alB, l_reg, pa0, pa1, pa2, pa3); PP_SB();
;     pv128(o, vb0 + VBUF, pa0, pa1, pa2, pa3);
;     __builtin_amdgcn_s_setprio(0);
;     __syncthreads();
.LBB0_521:
	v_cndmask_b32_e64 v96, v101, v142, s[8:9]
	v_mul_f32_e32 v96, 0xbe38aa3b, v96
	v_pk_fma_f32 v[80:81], v[80:81], s[90:91], v[96:97] op_sel_hi:[1,0,0]
	v_exp_f32_e32 v80, v80
	v_fmamk_f32 v82, v82, 0x3e38aa3b, v96
	v_exp_f32_e32 v81, v81
	v_fmamk_f32 v83, v83, 0x3e38aa3b, v96
	v_exp_f32_e32 v82, v82
	v_fmamk_f32 v95, v95, 0x3e38aa3b, v96
	v_fmamk_f32 v94, v94, 0x3e38aa3b, v96
	v_fmamk_f32 v93, v93, 0x3e38aa3b, v96
	v_fmamk_f32 v92, v92, 0x3e38aa3b, v96
	v_fmamk_f32 v91, v91, 0x3e38aa3b, v96
	v_fmamk_f32 v90, v90, 0x3e38aa3b, v96
	v_fmamk_f32 v89, v89, 0x3e38aa3b, v96
	v_fmamk_f32 v88, v88, 0x3e38aa3b, v96
	v_fmamk_f32 v87, v87, 0x3e38aa3b, v96
	v_fmamk_f32 v86, v86, 0x3e38aa3b, v96
	v_fmamk_f32 v85, v85, 0x3e38aa3b, v96
	v_fmamk_f32 v84, v84, 0x3e38aa3b, v96
	v_exp_f32_e32 v83, v83
	v_fmamk_f32 v79, v79, 0x3e38aa3b, v96
	v_fmamk_f32 v78, v78, 0x3e38aa3b, v96
	v_fmamk_f32 v77, v77, 0x3e38aa3b, v96
	v_fmamk_f32 v76, v76, 0x3e38aa3b, v96
	v_fmamk_f32 v75, v75, 0x3e38aa3b, v96
	v_fmamk_f32 v74, v74, 0x3e38aa3b, v96
	v_fmamk_f32 v73, v73, 0x3e38aa3b, v96
	v_fmamk_f32 v72, v72, 0x3e38aa3b, v96
	v_fmamk_f32 v71, v71, 0x3e38aa3b, v96
	v_fmamk_f32 v70, v70, 0x3e38aa3b, v96
	v_fmamk_f32 v69, v69, 0x3e38aa3b, v96
	v_fmamk_f32 v68, v68, 0x3e38aa3b, v96
	v_fmamk_f32 v67, v67, 0x3e38aa3b, v96
	v_fmamk_f32 v66, v66, 0x3e38aa3b, v96
	v_fmamk_f32 v65, v65, 0x3e38aa3b, v96
	v_fmac_f32_e32 v96, 0x3e38aa3b, v64
	v_exp_f32_e32 v84, v84
	v_exp_f32_e32 v64, v96
	v_exp_f32_e32 v96, v65
	v_add_f32_e32 v65, 0, v80
	v_exp_f32_e32 v85, v85
	v_add_f32_e32 v65, v81, v65
	v_exp_f32_e32 v86, v86
	v_add_f32_e32 v65, v82, v65
	v_exp_f32_e32 v87, v87
	v_add_f32_e32 v65, v83, v65
	v_exp_f32_e32 v88, v88
	v_add_f32_e32 v65, v84, v65
	v_exp_f32_e32 v89, v89
	v_add_f32_e32 v65, v85, v65
	v_exp_f32_e32 v90, v90
	v_add_f32_e32 v65, v86, v65
	v_exp_f32_e32 v91, v91
	v_add_f32_e32 v65, v87, v65
	v_exp_f32_e32 v92, v92
	v_add_f32_e32 v65, v88, v65
	v_exp_f32_e32 v93, v93
	v_add_f32_e32 v65, v89, v65
	v_exp_f32_e32 v94, v94
	v_add_f32_e32 v65, v90, v65
	v_exp_f32_e32 v95, v95
	v_add_f32_e32 v65, v91, v65
	v_add_f32_e32 v65, v92, v65
	v_add_f32_e32 v65, v93, v65
	v_exp_f32_e32 v66, v66
	v_add_f32_e32 v65, v94, v65
	v_exp_f32_e32 v101, v67
	v_add_f32_e32 v65, v95, v65
	v_exp_f32_e32 v102, v68
	v_add_f32_e32 v65, v64, v65
	v_exp_f32_e32 v103, v69
	v_add_f32_e32 v65, v96, v65
	v_exp_f32_e32 v104, v70
	v_add_f32_e32 v65, v66, v65
	v_exp_f32_e32 v105, v71
	v_add_f32_e32 v65, v101, v65
	v_exp_f32_e32 v106, v72
	v_add_f32_e32 v65, v102, v65
	v_exp_f32_e32 v107, v73
	v_add_f32_e32 v65, v103, v65
	v_exp_f32_e32 v108, v74
	v_add_f32_e32 v65, v104, v65
	v_exp_f32_e32 v109, v75
	v_add_f32_e32 v65, v105, v65
	v_exp_f32_e32 v110, v76
	v_add_f32_e32 v65, v106, v65
	v_exp_f32_e32 v111, v77
	v_add_f32_e32 v65, v107, v65
	v_exp_f32_e32 v112, v78
	v_add_f32_e32 v65, v108, v65
	v_exp_f32_e32 v113, v79
	v_add_f32_e32 v65, v109, v65
	v_add_f32_e32 v65, v110, v65
	v_add_f32_e32 v65, v111, v65
	v_add_f32_e32 v65, v112, v65
	v_add_f32_e32 v65, v113, v65
	v_mov_b32_e32 v67, v65
	v_cvt_pk_bf16_f32 v68, v80, v81
	v_cvt_pk_bf16_f32 v69, v82, v83
	v_cvt_pk_bf16_f32 v70, v84, v85
	v_cvt_pk_bf16_f32 v71, v86, v87
	s_nop 1
	v_permlane32_swap_b32_e32 v65, v67
	v_permlane32_swap_b32_e32 v68, v70
	v_permlane32_swap_b32_e32 v69, v71
	v_cvt_pk_bf16_f32 v72, v88, v89
	v_cvt_pk_bf16_f32 v73, v90, v91
	v_cvt_pk_bf16_f32 v74, v92, v93
	v_cvt_pk_bf16_f32 v75, v94, v95
	v_cvt_pk_bf16_f32 v76, v64, v96
	v_cvt_pk_bf16_f32 v77, v66, v101
	v_cvt_pk_bf16_f32 v78, v102, v103
	v_cvt_pk_bf16_f32 v79, v104, v105
	v_cvt_pk_bf16_f32 v80, v106, v107
	v_cvt_pk_bf16_f32 v81, v108, v109
	v_cvt_pk_bf16_f32 v82, v110, v111
	v_cvt_pk_bf16_f32 v83, v112, v113
	s_nop 0
	v_permlane32_swap_b32_e32 v72, v74
	v_permlane32_swap_b32_e32 v73, v75
	v_permlane32_swap_b32_e32 v76, v78
	v_permlane32_swap_b32_e32 v77, v79
	v_permlane32_swap_b32_e32 v80, v82
	v_permlane32_swap_b32_e32 v81, v83
	ds_read_b64_tr_b16 v[84:85], v177 offset:0
	ds_read_b64_tr_b16 v[86:87], v177 offset:0x800
	ds_read_b64_tr_b16 v[88:89], v177 offset:0x1000
	ds_read_b64_tr_b16 v[90:91], v177 offset:0x1800
	ds_read_b64_tr_b16 v[92:93], v177 offset:0x2000
	ds_read_b64_tr_b16 v[94:95], v177 offset:0x2800
	ds_read_b64_tr_b16 v[102:103], v177 offset:0x3000
	ds_read_b64_tr_b16 v[104:105], v177 offset:0x3800
	s_waitcnt lgkmcnt(0)
	s_nop 0
	v_mfma_f32_32x32x16_bf16 v[48:63], v[68:71], v[84:87], v[48:63]
	ds_read_b64_tr_b16 v[84:85], v177 offset:0x200
	ds_read_b64_tr_b16 v[86:87], v177 offset:0xa00
	v_mfma_f32_32x32x16_bf16 v[48:63], v[72:75], v[88:91], v[48:63]
	ds_read_b64_tr_b16 v[88:89], v177 offset:0x1200
	ds_read_b64_tr_b16 v[90:91], v177 offset:0x1a00
	v_mfma_f32_32x32x16_bf16 v[48:63], v[76:79], v[92:95], v[48:63]
	ds_read_b64_tr_b16 v[92:93], v177 offset:0x2200
	ds_read_b64_tr_b16 v[94:95], v177 offset:0x2a00
	v_mfma_f32_32x32x16_bf16 v[48:63], v[80:83], v[102:105], v[48:63]
	ds_read_b64_tr_b16 v[102:103], v177 offset:0x3200
	ds_read_b64_tr_b16 v[104:105], v177 offset:0x3a00
	s_waitcnt lgkmcnt(0)
	v_mfma_f32_32x32x16_bf16 v[32:47], v[68:71], v[84:87], v[32:47]
	ds_read_b64_tr_b16 v[84:85], v177 offset:0x400
	ds_read_b64_tr_b16 v[86:87], v177 offset:0xc00
	v_mfma_f32_32x32x16_bf16 v[32:47], v[72:75], v[88:91], v[32:47]
	ds_read_b64_tr_b16 v[88:89], v177 offset:0x1400
	ds_read_b64_tr_b16 v[90:91], v177 offset:0x1c00
	v_mfma_f32_32x32x16_bf16 v[32:47], v[76:79], v[92:95], v[32:47]
	ds_read_b64_tr_b16 v[92:93], v177 offset:0x2400
	ds_read_b64_tr_b16 v[94:95], v177 offset:0x2c00
	v_mfma_f32_32x32x16_bf16 v[32:47], v[80:83], v[102:105], v[32:47]
	ds_read_b64_tr_b16 v[102:103], v177 offset:0x3400
	ds_read_b64_tr_b16 v[104:105], v177 offset:0x3c00
	s_waitcnt lgkmcnt(0)
	v_mfma_f32_32x32x16_bf16 v[16:31], v[68:71], v[84:87], v[16:31]
	ds_read_b64_tr_b16 v[84:85], v177 offset:0x600
	ds_read_b64_tr_b16 v[86:87], v177 offset:0xe00
	v_mfma_f32_32x32x16_bf16 v[16:31], v[72:75], v[88:91], v[16:31]
	ds_read_b64_tr_b16 v[88:89], v177 offset:0x1600
	ds_read_b64_tr_b16 v[90:91], v177 offset:0x1e00
	v_mfma_f32_32x32x16_bf16 v[16:31], v[76:79], v[92:95], v[16:31]
	ds_read_b64_tr_b16 v[92:93], v177 offset:0x2600
	ds_read_b64_tr_b16 v[94:95], v177 offset:0x2e00
	v_mfma_f32_32x32x16_bf16 v[16:31], v[80:83], v[102:105], v[16:31]
	ds_read_b64_tr_b16 v[102:103], v177 offset:0x3600
	ds_read_b64_tr_b16 v[104:105], v177 offset:0x3e00
	s_waitcnt lgkmcnt(0)
	v_mfma_f32_32x32x16_bf16 v[0:15], v[68:71], v[84:87], v[0:15]
	v_mfma_f32_32x32x16_bf16 v[0:15], v[72:75], v[88:91], v[0:15]
	v_mfma_f32_32x32x16_bf16 v[0:15], v[76:79], v[92:95], v[0:15]
	v_mfma_f32_32x32x16_bf16 v[0:15], v[80:83], v[102:105], v[0:15]
	s_setprio 0
	v_mov_b32_e32 v64, v196
	s_barrier
; #define LAS __attribute__((address_space(3)))
; DI void row_rcp(LAS unsigned char* lds, float l, float (&rli)[16]) {
;     int tid_ = threadIdx.x; asm volatile("" : "+v"(tid_));
;     const int tid = tid_, wid = tid >> 6, lane = tid & 63, r32 = lane & 31, hi = lane >> 5;
;     LAS float* wsf = (LAS float*)(lds + L_WS) + wid * 64;
;     if (hi == 0) wsf[32 + r32] = l;
	s_nop 0
	v_bfe_u32 v68, v64, 5, 1
	v_and_b32_e32 v66, 0x3fffffc0, v64
	v_lshl_add_u32 v69, v66, 2, 0
	v_cmp_eq_u32_e32 vcc, 0, v68
	s_and_saveexec_b64 s[0:1], vcc
	s_cbranch_execz .LBB0_460
	v_and_b32_e32 v64, 31, v64
	v_lshl_add_u32 v70, v64, 2, v69
	v_mul_f32_e32 v64, v176, v143
	v_add_f32_e32 v66, v98, v99
	v_pk_add_f32 v[64:65], v[64:65], v[66:67]
	s_nop 0
	v_fmac_f32_e32 v65, v64, v100
	ds_write_b32 v70, v65 offset:51328
	s_branch .LBB0_460
